# sg item: prologue tile loads batched; epilogue u/gate loads hoisted with counted waits
# speedup vs baseline: 1.1756x; 1.0043x over previous
; DI void sg_item(const Params& p, int l, int item, char* lds, int dry) {
;     ...
;   const size_t tokbase = (size_t)b * S_ + chunk * 128;
; #pragma unroll
;   for (int i = 0; i < 4; ++i) {
;     const int id = tid + 256 * i, row = id >> 3, c = id & 7;
;     *(uint4*)(vn + row * 72 + c * 8) = *(const uint4*)(p.z + (tokbase + row) * ZS + VD + g * 64 + c * 8);
;   }
;   __syncthreads();
;   const int t = 32 * w + r;
;   const float* wr = p.w_spatial + (((size_t)(l * 8 + g) * 128) + t) * 128;
;   const int q4 = (lane & 15) >> 2, p4 = lane & 3, blk = (lane >> 4) & 1;
;   f32x16 acc[2];
; #pragma unroll
;   for (int i = 0; i < 16; ++i) { acc[0][i] = 0.f; acc[1][i] = 0.f; }
;   const int nks = 2 * (w + 1);
;   for (int ks = 0; ks < nks; ++ks) {
;     const int s0 = ks * 16 + 8 * h;
; __global__ void __launch_bounds__(256, 2) hybrid_fwd(Params p) {
;     ...
;           const int it = pop_item(ctr2, &slot);
;           if (it >= 3072) break;
;           if (it < 2048) { if (!dry || (P3_MASK & 4)) lru_item(p, l, it, 2, lds, dry); }
;           else { if (!dry || (P3_MASK & 8)) sg_item(p, l, it - 2048, lds, dry); }
.LBB0_778:
	s_or_b64 exec, exec, s[0:1]
	s_waitcnt lgkmcnt(0)
	s_barrier
	ds_read_b32 v0, v221
	s_movk_i32 s0, 0xbff
	s_waitcnt lgkmcnt(0)
	v_cmp_lt_i32_e32 vcc, s0, v0
	v_readfirstlane_b32 s5, v0
	s_mov_b64 s[0:1], -1
	s_cbranch_vccnz .LBB0_773
	s_and_b32 s4, s5, 7
	s_lshl_b32 s6, s4, 6
	s_cmpk_gt_i32 s5, 0x7ff
	s_cbranch_scc0 .LBB0_913
	v_mov_b32_e32 v38, v209
	s_lshl_b32 s0, s5, 4
	v_readlane_b32 s80, v253, 12
	s_and_b32 s7, s0, 0x3f80
	v_ashrrev_i32_e32 v4, 3, v38
	v_readlane_b32 s86, v253, 18
	v_readlane_b32 s87, v253, 19
	v_add_u32_e32 v2, s7, v4
	v_lshlrev_b32_e32 v0, 4, v38
	v_mov_b64_e32 v[6:7], s[86:87]
	v_mad_i64_i32 v[2:3], s[0:1], v2, s75, v[6:7]
	s_lshl_b32 s18, s6, 1
	v_and_b32_e32 v0, 0x70, v0
	v_lshl_add_u64 v[2:3], v[2:3], 0, s[18:19]
	v_lshl_add_u64 v[2:3], v[2:3], 0, v[0:1]
	s_movk_i32 s2, 0x2000
	v_add_co_u32_e32 v2, vcc, s2, v2
	v_mad_u64_u32 v[8:9], s[0:1], v4, s76, v[0:1]
	v_mov_b32_e32 v244, v8
	s_nop 0
	v_addc_co_u32_e32 v3, vcc, 0, v3, vcc
	global_load_dwordx4 v[228:231], v[2:3], off offset:2560
	v_ashrrev_i32_e32 v34, 6, v38
	v_and_b32_e32 v39, 31, v38
	v_lshlrev_b32_e32 v40, 5, v34
	v_bfe_u32 v37, v38, 5, 1
	v_mov_b32_e32 v33, 0
	s_movk_i32 s96, 0x2000
	s_waitcnt vmcnt(32)
	v_or_b32_e32 v36, v40, v39
	s_lshl_b32 s9, s4, 7
	v_mov_b32_e32 v32, v33
	v_mov_b32_e32 v31, v33
	v_mov_b32_e32 v30, v33
	v_mov_b32_e32 v29, v33
	v_mov_b32_e32 v28, v33
	v_mov_b32_e32 v27, v33
	v_mov_b32_e32 v26, v33
	v_mov_b32_e32 v25, v33
	v_mov_b32_e32 v24, v33
	v_mov_b32_e32 v23, v33
	v_mov_b32_e32 v22, v33
	v_mov_b32_e32 v21, v33
	v_mov_b32_e32 v20, v33
	v_mov_b32_e32 v19, v33
	v_mov_b32_e32 v18, v33
	v_mov_b32_e32 v17, v33
	v_mov_b32_e32 v16, v33
	v_mov_b32_e32 v15, v33
	v_mov_b32_e32 v14, v33
	v_mov_b32_e32 v13, v33
	v_mov_b32_e32 v12, v33
	v_mov_b32_e32 v11, v33
	v_mov_b32_e32 v10, v33
	v_readlane_b32 s81, v253, 13
	v_readlane_b32 s82, v253, 14
	v_readlane_b32 s83, v253, 15
	v_readlane_b32 s84, v253, 16
	v_readlane_b32 s85, v253, 17
	v_readlane_b32 s88, v253, 20
	v_readlane_b32 s89, v253, 21
	v_readlane_b32 s90, v253, 22
	v_readlane_b32 s91, v253, 23
	v_readlane_b32 s92, v253, 24
	v_readlane_b32 s93, v253, 25
	v_readlane_b32 s94, v253, 26
	v_readlane_b32 s95, v253, 27
	v_add_u32_e32 v2, 0x100, v38
	v_ashrrev_i32_e32 v4, 3, v2
	v_add_u32_e32 v2, s7, v4
	v_mad_i64_i32 v[2:3], s[0:1], v2, s75, v[6:7]
	v_lshl_add_u64 v[2:3], v[2:3], 0, s[18:19]
	v_lshl_add_u64 v[2:3], v[2:3], 0, v[0:1]
	v_add_co_u32_e32 v2, vcc, s2, v2
	v_mad_u64_u32 v[8:9], s[0:1], v4, s76, v[0:1]
	v_mov_b32_e32 v245, v8
	s_nop 0
	v_addc_co_u32_e32 v3, vcc, 0, v3, vcc
	global_load_dwordx4 v[232:235], v[2:3], off offset:2560
	v_add_u32_e32 v2, 0x200, v38
	v_ashrrev_i32_e32 v4, 3, v2
	v_add_u32_e32 v2, s7, v4
	v_mad_i64_i32 v[2:3], s[0:1], v2, s75, v[6:7]
	v_lshl_add_u64 v[2:3], v[2:3], 0, s[18:19]
	v_lshl_add_u64 v[2:3], v[2:3], 0, v[0:1]
	v_add_co_u32_e32 v2, vcc, s2, v2
	v_mad_u64_u32 v[8:9], s[0:1], v4, s76, v[0:1]
	v_mov_b32_e32 v246, v8
	s_nop 0
	v_addc_co_u32_e32 v3, vcc, 0, v3, vcc
	global_load_dwordx4 v[236:239], v[2:3], off offset:2560
	v_mov_b32_e32 v9, v33
	v_add_u32_e32 v2, 0x300, v38
	v_ashrrev_i32_e32 v4, 3, v2
	v_add_u32_e32 v2, s7, v4
	v_mad_i64_i32 v[2:3], s[0:1], v2, s75, v[6:7]
	v_lshl_add_u64 v[2:3], v[2:3], 0, s[18:19]
	v_lshl_add_u64 v[2:3], v[2:3], 0, v[0:1]
	v_add_co_u32_e32 v2, vcc, s2, v2
	v_mad_u64_u32 v[6:7], s[0:1], v4, s76, v[0:1]
	s_nop 0
	v_addc_co_u32_e32 v3, vcc, 0, v3, vcc
	global_load_dwordx4 v[240:243], v[2:3], off offset:2560
	v_cmp_lt_i32_e32 vcc, -1, v34
	v_lshlrev_b32_e32 v0, 3, v37
	v_mov_b32_e32 v8, v33
	v_mov_b32_e32 v7, v33
	s_waitcnt vmcnt(3)
	ds_write_b128 v244, v[228:231]
	s_waitcnt vmcnt(2)
	ds_write_b128 v245, v[232:235]
	s_waitcnt vmcnt(1)
	ds_write_b128 v246, v[236:239]
	s_waitcnt vmcnt(0)
	ds_write_b128 v6, v[240:243]
	v_mov_b32_e32 v6, v33
	v_mov_b32_e32 v5, v33
	v_mov_b32_e32 v4, v33
	v_mov_b32_e32 v3, v33
	v_mov_b32_e32 v2, v33
	s_waitcnt lgkmcnt(0)
	s_barrier
	s_and_saveexec_b64 s[0:1], vcc
	s_cbranch_execz .LBB0_784
	v_bfe_u32 v2, v38, 2, 2
	v_lshlrev_b32_e32 v4, 1, v38
	v_mul_u32_u24_e32 v3, 0x480, v37
	v_mul_u32_u24_e32 v2, 0x90, v2
	v_and_b32_e32 v4, 32, v4
	v_add3_u32 v2, v3, v2, v4
	v_and_b32_e32 v3, 3, v38
	v_lshlrev_b32_e32 v3, 3, v3
	s_movk_i32 s2, 0x280
	v_add3_u32 v37, v2, v3, s2
	v_add_u32_e32 v2, v40, v39
	v_ashrrev_i32_e32 v3, 31, v2
	s_add_i32 s2, s8, s9
	s_mov_b32 s3, s19
	v_lshl_add_u64 v[2:3], v[2:3], 0, s[2:3]
	v_lshlrev_b64 v[2:3], 9, v[2:3]
	v_readlane_b32 s2, v253, 32
	v_and_or_b32 v2, v38, 32, v2
	v_readlane_b32 s3, v253, 33
	v_mov_b32_e32 v35, v36
	v_lshl_add_u32 v34, v34, 1, 2
	v_lshl_add_u64 v[38:39], s[2:3], 0, v[2:3]
	v_mov_b32_e32 v2, 0
	s_mov_b64 s[2:3], 0
	v_mov_b32_e32 v40, v0
	v_mov_b32_e32 v3, v2
	v_mov_b32_e32 v4, v2
	v_mov_b32_e32 v5, v2
	v_mov_b32_e32 v6, v2
	v_mov_b32_e32 v7, v2
	v_mov_b32_e32 v8, v2
	v_mov_b32_e32 v9, v2
	v_mov_b32_e32 v10, v2
	v_mov_b32_e32 v11, v2
	v_mov_b32_e32 v12, v2
	v_mov_b32_e32 v13, v2
	v_mov_b32_e32 v14, v2
	v_mov_b32_e32 v15, v2
	v_mov_b32_e32 v16, v2
	v_mov_b32_e32 v17, v2
	v_mov_b32_e32 v18, v2
	v_mov_b32_e32 v19, v2
	v_mov_b32_e32 v20, v2
	v_mov_b32_e32 v21, v2
	v_mov_b32_e32 v22, v2
	v_mov_b32_e32 v23, v2
	v_mov_b32_e32 v24, v2
	v_mov_b32_e32 v25, v2
	v_mov_b32_e32 v26, v2
	v_mov_b32_e32 v27, v2
	v_mov_b32_e32 v28, v2
	v_mov_b32_e32 v29, v2
	v_mov_b32_e32 v30, v2
	v_mov_b32_e32 v31, v2
	v_mov_b32_e32 v32, v2
	v_mov_b32_e32 v33, v2
	s_mov_b32 s10, 0x5040100
	global_load_dwordx4 v[96:99], v[38:39], off offset:-16
	global_load_dwordx4 v[100:103], v[38:39], off
	global_load_dwordx4 v[104:107], v[38:39], off offset:48
	global_load_dwordx4 v[108:111], v[38:39], off offset:64
	global_load_dwordx4 v[112:115], v[38:39], off offset:112
	global_load_dwordx4 v[116:119], v[38:39], off offset:128
	global_load_dwordx4 v[120:123], v[38:39], off offset:176
	global_load_dwordx4 v[124:127], v[38:39], off offset:192
	global_load_dwordx4 v[128:131], v[38:39], off offset:240
	global_load_dwordx4 v[132:135], v[38:39], off offset:256
	global_load_dwordx4 v[136:139], v[38:39], off offset:304
	global_load_dwordx4 v[140:143], v[38:39], off offset:320
	global_load_dwordx4 v[144:147], v[38:39], off offset:368
	global_load_dwordx4 v[148:151], v[38:39], off offset:384
	global_load_dwordx4 v[152:155], v[38:39], off offset:432
	global_load_dwordx4 v[156:159], v[38:39], off offset:448

; DI unsigned pk2(float a, float b) { f2_t v = {a, b}; bf2_t r = __builtin_convertvector(v, bf2_t); return __builtin_bit_cast(unsigned, r); }
; DI float bflo(unsigned u) { return (float)__builtin_bit_cast(bf2_t, u)[0]; }
; DI float siluf_(float x) { return x / (1.f + __expf(-x)); }
; DI float geluf_(float x) { return 0.5f * x * (1.f + erff(x * 0.70710678118654752f)); }
; DI void sg_item(const Params& p, int l, int item, char* lds, int dry) {
;     ...
;   const float bsv = p.b_spatial[(l * 8 + g) * 128 + t];
;   u16* zr = p.z + (tokbase + t) * ZS;
; #pragma unroll
;   for (int db = 0; db < 2; ++db)
; #pragma unroll
;     for (int a4 = 0; a4 < 4; ++a4) {
;       const int d = db * 32 + 8 * a4 + 4 * h;
;       const uint2 uv = *(const uint2*)(zr + UD + g * 64 + d);
;       uint2* gp = (uint2*)(zr + GD + g * 64 + d);
;       const uint2 gv = *gp;
;       uint2 o;
;       o.x = pk2(geluf_(bflo(uv.x)) * (acc[db][4 * a4] + bsv) * siluf_(bflo(gv.x)),
.LBB0_784:
	s_or_b64 exec, exec, s[0:1]
	s_or_b32 s0, s9, s8
	v_add_u32_e32 v34, s0, v36
	v_readlane_b32 s80, v251, 18
	v_ashrrev_i32_e32 v35, 31, v34
	v_readlane_b32 s81, v251, 19
	v_readlane_b32 s82, v251, 20
	v_readlane_b32 s83, v251, 21
	v_readlane_b32 s84, v251, 22
	v_readlane_b32 s85, v251, 23
	v_readlane_b32 s86, v251, 24
	v_readlane_b32 s87, v251, 25
	v_readlane_b32 s88, v251, 26
	v_readlane_b32 s89, v251, 27
	v_readlane_b32 s90, v251, 28
	v_readlane_b32 s91, v251, 29
	v_readlane_b32 s92, v251, 30
	v_readlane_b32 s93, v251, 31
	v_readlane_b32 s94, v251, 32
	v_readlane_b32 s95, v251, 33
	v_lshl_add_u64 v[34:35], v[34:35], 2, s[92:93]
	v_readlane_b32 s80, v253, 12
	v_readlane_b32 s86, v253, 18
	v_readlane_b32 s87, v253, 19
	global_load_dword v34, v[34:35], off
	v_add_u32_e32 v35, s7, v36
	v_mov_b64_e32 v[36:37], s[86:87]
	v_mad_i64_i32 v[36:37], s[0:1], v35, s75, v[36:37]
	v_lshl_add_u64 v[36:37], v[36:37], 0, s[18:19]
	v_lshl_add_u64 v[36:37], v[36:37], 0, v[0:1]
	v_add_co_u32_e32 v40, vcc, 0x2000, v36
	v_readlane_b32 s81, v253, 13
	s_nop 0
	v_addc_co_u32_e32 v41, vcc, 0, v37, vcc
	global_load_dwordx2 v[38:39], v[40:41], off offset:1536
	s_nop 0
	v_mov_b32_e32 v198, v40
	v_mov_b32_e32 v199, v41
	global_load_dwordx2 v[40:41], v[40:41], off offset:3584
	global_load_dwordx2 v[170:171], v[198:199], off offset:1552
	global_load_dwordx2 v[172:173], v[198:199], off offset:3600
	global_load_dwordx2 v[174:175], v[198:199], off offset:1568
	global_load_dwordx2 v[176:177], v[198:199], off offset:3616
	global_load_dwordx2 v[178:179], v[198:199], off offset:1584
	global_load_dwordx2 v[180:181], v[198:199], off offset:3632
	global_load_dwordx2 v[182:183], v[198:199], off offset:1600
	global_load_dwordx2 v[184:185], v[198:199], off offset:3648
	global_load_dwordx2 v[186:187], v[198:199], off offset:1616
	global_load_dwordx2 v[188:189], v[198:199], off offset:3664
	global_load_dwordx2 v[190:191], v[198:199], off offset:1632
	global_load_dwordx2 v[192:193], v[198:199], off offset:3680
	global_load_dwordx2 v[194:195], v[198:199], off offset:1648
	global_load_dwordx2 v[196:197], v[198:199], off offset:3696
	v_readlane_b32 s82, v253, 14
	v_readlane_b32 s83, v253, 15
	v_readlane_b32 s84, v253, 16
	v_readlane_b32 s85, v253, 17
	v_readlane_b32 s88, v253, 20
	v_readlane_b32 s89, v253, 21
	v_readlane_b32 s90, v253, 22
	v_readlane_b32 s91, v253, 23
	v_readlane_b32 s92, v253, 24
	v_readlane_b32 s93, v253, 25
	v_readlane_b32 s94, v253, 26
	v_readlane_b32 s95, v253, 27
	s_waitcnt vmcnt(15)
	v_cvt_f32_f16_e32 v0, v38
	v_mul_f32_e32 v35, 0x3f3504f3, v0
	v_cmp_nlt_f32_e64 s[0:1], |v35|, 1.0
	s_and_saveexec_b64 s[2:3], s[0:1]
	s_xor_b64 s[0:1], exec, s[2:3]
	s_cbranch_execz .LBB0_786
	v_fma_f32 v42, |v35|, s77, v224
	s_mov_b32 s2, 0x3b7cd369
	v_fma_f32 v42, |v35|, v42, s2
	s_mov_b32 s2, 0xbcc618b2
	v_fma_f32 v42, |v35|, v42, s2
	s_mov_b32 s2, 0x3dda74e4
	v_fma_f32 v42, |v35|, v42, s2
	s_mov_b32 s2, 0x3f228afd
	v_fma_f32 v42, |v35|, v42, s2
	s_mov_b32 s2, 0x3e03c728
	v_fma_f32 v42, |v35|, v42, s2
	v_fma_f32 v42, |v35|, v42, |v35|
	v_mul_f32_e32 v43, 0xbfb8aa3b, v42
	s_mov_b32 s2, 0xbfb8aa3b
	v_fma_f32 v44, v42, s2, -v43
	v_rndne_f32_e32 v45, v43
	v_fmac_f32_e32 v44, 0xb2a5705f, v42
	v_sub_f32_e32 v43, v43, v45
	v_add_f32_e32 v43, v43, v44
	v_cvt_i32_f32_e32 v44, v45
	v_exp_f32_e32 v43, v43
	s_mov_b32 s2, 0x42ce8ed0
	v_cmp_nlt_f32_e32 vcc, s2, v42
	s_mov_b32 s2, 0xc2b17218
	v_ldexp_f32 v43, v43, v44
	v_cndmask_b32_e32 v43, 0, v43, vcc
	v_cmp_ngt_f32_e32 vcc, s2, v42
	s_nop 1
	v_cndmask_b32_e32 v42, v225, v43, vcc
	v_sub_f32_e32 v44, 1.0, v42

; DI unsigned pk2(float a, float b) { f2_t v = {a, b}; bf2_t r = __builtin_convertvector(v, bf2_t); return __builtin_bit_cast(unsigned, r); }
; DI float bflo(unsigned u) { return (float)__builtin_bit_cast(bf2_t, u)[0]; }
; DI float bfhi(unsigned u) { return (float)__builtin_bit_cast(bf2_t, u)[1]; }
; DI float siluf_(float x) { return x / (1.f + __expf(-x)); }
; DI float geluf_(float x) { return 0.5f * x * (1.f + erff(x * 0.70710678118654752f)); }
; DI void sg_item(const Params& p, int l, int item, char* lds, int dry) {
;     ...
;     for (int a4 = 0; a4 < 4; ++a4) {
;       const int d = db * 32 + 8 * a4 + 4 * h;
;       const uint2 uv = *(const uint2*)(zr + UD + g * 64 + d);
;       uint2* gp = (uint2*)(zr + GD + g * 64 + d);
;       const uint2 gv = *gp;
;       uint2 o;
;       o.x = pk2(geluf_(bflo(uv.x)) * (acc[db][4 * a4] + bsv) * siluf_(bflo(gv.x)),
;                 geluf_(bfhi(uv.x)) * (acc[db][4 * a4 + 1] + bsv) * siluf_(bfhi(gv.x)));
;       o.y = pk2(geluf_(bflo(uv.y)) * (acc[db][4 * a4 + 2] + bsv) * siluf_(bflo(gv.y)),
;                 geluf_(bfhi(uv.y)) * (acc[db][4 * a4 + 3] + bsv) * siluf_(bfhi(gv.y)));
;       if (dry) gp = (uint2*)(p.blkscr + (size_t)blockIdx.x * 8 * 256 + tid + ((db * 4 + a4) >> 1) * 256) + (a4 & 1);
;       *gp = o;
.LBB0_798:
	s_andn2_saveexec_b64 s[0:1], s[0:1]
	v_mul_f32_e32 v38, v46, v46
	v_fmamk_f32 v39, v38, 0xba1345e1, v220
	v_fmaak_f32 v39, v38, v39, 0xbcdac9b8
	v_fmaak_f32 v39, v38, v39, 0x3de703be
	v_fmaak_f32 v39, v38, v39, 0xbec09330
	v_fmaak_f32 v38, v38, v39, 0x3e0375d0
	v_fma_f32 v48, |v46|, v38, |v46|
	s_or_b64 exec, exec, s[0:1]
	s_brev_b32 s2, -2
	v_bfi_b32 v49, s2, v51, v49
	v_mul_f32_e32 v50, 0.5, v50
	v_add_f32_e32 v49, 1.0, v49
	v_mul_f32_e32 v49, v50, v49
	v_add_f32_e32 v20, v34, v20
	v_mul_f32_e32 v20, v20, v49
	s_waitcnt vmcnt(14)
	v_cvt_f32_f16_e32 v49, v41
	s_mov_b64 s[0:1], 0x2600
	v_lshl_add_u64 v[38:39], v[36:37], 0, s[0:1]
	s_mov_b64 s[0:1], 0x2e00
	v_mul_f32_e32 v50, 0xbfb8aa3b, v49
	v_exp_f32_e32 v50, v50
	v_lshl_add_u64 v[36:37], v[36:37], 0, s[0:1]
	v_mul_f32_e32 v0, 0.5, v0
	v_add_f32_e32 v18, v34, v18
	v_add_f32_e32 v50, 1.0, v50
	v_div_scale_f32 v51, s[0:1], v50, v50, v49
	v_rcp_f32_e32 v52, v51
	v_mov_b32_e32 v210, v19
	v_fma_f32 v53, -v51, v52, 1.0
	v_fmac_f32_e32 v52, v53, v52
	v_div_scale_f32 v53, vcc, v49, v50, v49
	v_mul_f32_e32 v54, v53, v52
	v_fma_f32 v55, -v51, v54, v53
	v_fmac_f32_e32 v54, v55, v52
	v_fma_f32 v51, -v51, v54, v53
	v_div_fmas_f32 v51, v51, v52, v54
	v_div_fixup_f32 v49, v51, v50, v49
	v_mul_f32_e32 v49, v49, v20
	v_bfi_b32 v20, s2, v44, v35
	v_add_f32_e32 v20, 1.0, v20
	v_mul_f32_e32 v0, v0, v20
	v_mul_f32_e32 v0, v18, v0
	v_cvt_f32_f16_e32 v18, v40
	v_mul_f32_e32 v20, 0xbfb8aa3b, v18
	v_exp_f32_e32 v20, v20
	s_nop 0
	v_add_f32_e32 v20, 1.0, v20
	v_div_scale_f32 v35, s[0:1], v20, v20, v18
	v_rcp_f32_e32 v44, v35
	s_nop 0
	v_fma_f32 v50, -v35, v44, 1.0
	v_fmac_f32_e32 v44, v50, v44
	v_div_scale_f32 v50, vcc, v18, v20, v18
	v_mul_f32_e32 v51, v50, v44
	v_fma_f32 v52, -v35, v51, v50
	v_fmac_f32_e32 v51, v52, v44
	v_fma_f32 v35, -v35, v51, v50
	v_div_fmas_f32 v35, v35, v44, v51
	v_div_fixup_f32 v18, v35, v20, v18
	v_bfi_b32 v35, s2, v45, v43
	v_mul_f32_e32 v0, v18, v0
	v_mul_f32_e32 v20, 0.5, v42
	v_pk_add_f32 v[18:19], v[34:35], v[210:211]
	v_mov_b32_e32 v210, v21
	v_mul_f32_e32 v19, v20, v19
	v_mul_f32_e32 v18, v18, v19
	v_cvt_f32_f16_sdwa v19, v40 dst_sel:DWORD dst_unused:UNUSED_PAD src0_sel:WORD_1
	v_mul_f32_e32 v20, 0xbfb8aa3b, v19
	v_exp_f32_e32 v20, v20
	s_nop 0
	v_add_f32_e32 v20, 1.0, v20
	v_div_scale_f32 v35, s[0:1], v20, v20, v19
	v_rcp_f32_e32 v40, v35
	s_nop 0
	v_fma_f32 v42, -v35, v40, 1.0
	v_fmac_f32_e32 v40, v42, v40
	v_div_scale_f32 v42, vcc, v19, v20, v19
	v_mul_f32_e32 v43, v42, v40
	v_fma_f32 v44, -v35, v43, v42
	v_fmac_f32_e32 v43, v44, v40
	v_fma_f32 v35, -v35, v43, v42
	v_div_fmas_f32 v35, v35, v40, v43
	v_div_fixup_f32 v19, v35, v20, v19
	v_mul_f32_e32 v18, v19, v18
	v_cvt_f32_f16_sdwa v19, v41 dst_sel:DWORD dst_unused:UNUSED_PAD src0_sel:WORD_1
	v_bfi_b32 v35, s2, v48, v46
	v_cvt_pk_f16_f32 v18, v0, v18
	v_mul_f32_e32 v0, 0.5, v47
	v_pk_add_f32 v[20:21], v[34:35], v[210:211]
	s_nop 0
	v_mul_f32_e32 v0, v0, v21
	v_mul_f32_e32 v0, v20, v0
	v_mul_f32_e32 v20, 0xbfb8aa3b, v19
	v_exp_f32_e32 v20, v20
	s_nop 0
	v_add_f32_e32 v20, 1.0, v20
	v_div_scale_f32 v21, s[0:1], v20, v20, v19
	v_rcp_f32_e32 v35, v21
	s_nop 0
	v_fma_f32 v40, -v21, v35, 1.0
	v_fmac_f32_e32 v35, v40, v35
	v_div_scale_f32 v40, vcc, v19, v20, v19
	v_mul_f32_e32 v41, v40, v35
	v_fma_f32 v42, -v21, v41, v40
	v_fmac_f32_e32 v41, v42, v35
	v_fma_f32 v21, -v21, v41, v40
	v_div_fmas_f32 v21, v21, v35, v41
	v_div_fixup_f32 v19, v21, v20, v19
	v_mul_f32_e32 v0, v19, v0
	v_cvt_pk_f16_f32 v19, v49, v0
	global_store_dwordx2 v[36:37], v[18:19], off
	s_nop 0
	s_waitcnt vmcnt(14)
	v_cvt_f32_f16_e32 v0, v170
	v_mul_f32_e32 v35, 0x3f3504f3, v0
	v_cmp_nlt_f32_e64 s[0:1], |v35|, 1.0
	s_and_saveexec_b64 s[2:3], s[0:1]
	s_xor_b64 s[0:1], exec, s[2:3]
	s_cbranch_execz .LBB0_802
	v_fma_f32 v40, |v35|, s77, v224
	s_mov_b32 s2, 0x3b7cd369
	v_fma_f32 v40, |v35|, v40, s2
	s_mov_b32 s2, 0xbcc618b2
	v_fma_f32 v40, |v35|, v40, s2
	s_mov_b32 s2, 0x3dda74e4
	v_fma_f32 v40, |v35|, v40, s2
	s_mov_b32 s2, 0x3f228afd
	v_fma_f32 v40, |v35|, v40, s2
	s_mov_b32 s2, 0x3e03c728
	v_fma_f32 v40, |v35|, v40, s2
	v_fma_f32 v40, |v35|, v40, |v35|
	v_mul_f32_e32 v41, 0xbfb8aa3b, v40
	s_mov_b32 s2, 0xbfb8aa3b
	v_fma_f32 v42, v40, s2, -v41
	v_rndne_f32_e32 v43, v41
	v_fmac_f32_e32 v42, 0xb2a5705f, v40
	v_sub_f32_e32 v41, v41, v43
	v_add_f32_e32 v41, v41, v42
	v_cvt_i32_f32_e32 v42, v43
	v_exp_f32_e32 v41, v41
	s_mov_b32 s2, 0x42ce8ed0
	v_cmp_nlt_f32_e32 vcc, s2, v40
	s_mov_b32 s2, 0xc2b17218
	v_ldexp_f32 v41, v41, v42
	v_cndmask_b32_e32 v41, 0, v41, vcc
	v_cmp_ngt_f32_e32 vcc, s2, v40
	s_nop 1
	v_cndmask_b32_e32 v40, v225, v41, vcc
	v_sub_f32_e32 v41, 1.0, v40
.LBB0_802:
	s_andn2_saveexec_b64 s[0:1], s[0:1]
	v_mul_f32_e32 v40, v35, v35
	v_fmamk_f32 v41, v40, 0xba1345e1, v220
	v_fmaak_f32 v41, v40, v41, 0xbcdac9b8
	v_fmaak_f32 v41, v40, v41, 0x3de703be
	v_fmaak_f32 v41, v40, v41, 0xbec09330
	v_fmaak_f32 v40, v40, v41, 0x3e0375d0
	v_fma_f32 v41, |v35|, v40, |v35|
	s_or_b64 exec, exec, s[0:1]
	v_cvt_f32_f16_sdwa v20, v170 dst_sel:DWORD dst_unused:UNUSED_PAD src0_sel:WORD_1
	v_mul_f32_e32 v40, 0x3f3504f3, v20
	v_cmp_nlt_f32_e64 s[0:1], |v40|, 1.0
	s_and_saveexec_b64 s[2:3], s[0:1]
	s_xor_b64 s[0:1], exec, s[2:3]
	s_cbranch_execz .LBB0_806
	v_fma_f32 v42, |v40|, s77, v224
	s_mov_b32 s2, 0x3b7cd369
	v_fma_f32 v42, |v40|, v42, s2
	s_mov_b32 s2, 0xbcc618b2
	v_fma_f32 v42, |v40|, v42, s2
	s_mov_b32 s2, 0x3dda74e4
	v_fma_f32 v42, |v40|, v42, s2
	s_mov_b32 s2, 0x3f228afd
	v_fma_f32 v42, |v40|, v42, s2
	s_mov_b32 s2, 0x3e03c728
	v_fma_f32 v42, |v40|, v42, s2
	v_fma_f32 v42, |v40|, v42, |v40|
	v_mul_f32_e32 v43, 0xbfb8aa3b, v42
	s_mov_b32 s2, 0xbfb8aa3b
	v_fma_f32 v44, v42, s2, -v43
	v_rndne_f32_e32 v45, v43
	v_fmac_f32_e32 v44, 0xb2a5705f, v42
	v_sub_f32_e32 v43, v43, v45
	v_add_f32_e32 v43, v43, v44
	v_cvt_i32_f32_e32 v44, v45
	v_exp_f32_e32 v43, v43
	s_mov_b32 s2, 0x42ce8ed0
	v_cmp_nlt_f32_e32 vcc, s2, v42
	s_mov_b32 s2, 0xc2b17218
	v_ldexp_f32 v43, v43, v44
	v_cndmask_b32_e32 v43, 0, v43, vcc
	v_cmp_ngt_f32_e32 vcc, s2, v42
	s_nop 1
	v_cndmask_b32_e32 v42, v225, v43, vcc
	v_sub_f32_e32 v42, 1.0, v42
; DI unsigned pk2(float a, float b) { f2_t v = {a, b}; bf2_t r = __builtin_convertvector(v, bf2_t); return __builtin_bit_cast(unsigned, r); }
; DI float bflo(unsigned u) { return (float)__builtin_bit_cast(bf2_t, u)[0]; }
; DI float bfhi(unsigned u) { return (float)__builtin_bit_cast(bf2_t, u)[1]; }
; DI float siluf_(float x) { return x / (1.f + __expf(-x)); }
; DI float geluf_(float x) { return 0.5f * x * (1.f + erff(x * 0.70710678118654752f)); }
; DI void sg_item(const Params& p, int l, int item, char* lds, int dry) {
;     ...
;     for (int a4 = 0; a4 < 4; ++a4) {
;       const int d = db * 32 + 8 * a4 + 4 * h;
;       const uint2 uv = *(const uint2*)(zr + UD + g * 64 + d);
;       uint2* gp = (uint2*)(zr + GD + g * 64 + d);
;       const uint2 gv = *gp;
;       uint2 o;
;       o.x = pk2(geluf_(bflo(uv.x)) * (acc[db][4 * a4] + bsv) * siluf_(bflo(gv.x)),
;                 geluf_(bfhi(uv.x)) * (acc[db][4 * a4 + 1] + bsv) * siluf_(bfhi(gv.x)));
;       o.y = pk2(geluf_(bflo(uv.y)) * (acc[db][4 * a4 + 2] + bsv) * siluf_(bflo(gv.y)),
;                 geluf_(bfhi(uv.y)) * (acc[db][4 * a4 + 3] + bsv) * siluf_(bfhi(gv.y)));
;       if (dry) gp = (uint2*)(p.blkscr + (size_t)blockIdx.x * 8 * 256 + tid + ((db * 4 + a4) >> 1) * 256) + (a4 & 1);
;       *gp = o;
.LBB0_806:
	s_andn2_saveexec_b64 s[0:1], s[0:1]
	v_mul_f32_e32 v42, v40, v40
	v_fmamk_f32 v43, v42, 0xba1345e1, v220
	v_fmaak_f32 v43, v42, v43, 0xbcdac9b8
	v_fmaak_f32 v43, v42, v43, 0x3de703be
	v_fmaak_f32 v43, v42, v43, 0xbec09330
	v_fmaak_f32 v42, v42, v43, 0x3e0375d0
	v_fma_f32 v42, |v40|, v42, |v40|
	s_or_b64 exec, exec, s[0:1]
	v_cvt_f32_f16_e32 v46, v171
	v_mul_f32_e32 v45, 0x3f3504f3, v46
	v_cmp_nlt_f32_e64 s[0:1], |v45|, 1.0
	s_and_saveexec_b64 s[2:3], s[0:1]
	s_xor_b64 s[0:1], exec, s[2:3]
	s_cbranch_execz .LBB0_810
	v_fma_f32 v43, |v45|, s77, v224
	s_mov_b32 s2, 0x3b7cd369
	v_fma_f32 v43, |v45|, v43, s2
	s_mov_b32 s2, 0xbcc618b2
	v_fma_f32 v43, |v45|, v43, s2
	s_mov_b32 s2, 0x3dda74e4
	v_fma_f32 v43, |v45|, v43, s2
	s_mov_b32 s2, 0x3f228afd
	v_fma_f32 v43, |v45|, v43, s2
	s_mov_b32 s2, 0x3e03c728
	v_fma_f32 v43, |v45|, v43, s2
	v_fma_f32 v43, |v45|, v43, |v45|
	v_mul_f32_e32 v44, 0xbfb8aa3b, v43
	s_mov_b32 s2, 0xbfb8aa3b
	v_fma_f32 v47, v43, s2, -v44
	v_rndne_f32_e32 v48, v44
	v_fmac_f32_e32 v47, 0xb2a5705f, v43
	v_sub_f32_e32 v44, v44, v48
	v_add_f32_e32 v44, v44, v47
	v_cvt_i32_f32_e32 v47, v48
	v_exp_f32_e32 v44, v44
	s_mov_b32 s2, 0x42ce8ed0
	v_cmp_nlt_f32_e32 vcc, s2, v43
	s_mov_b32 s2, 0xc2b17218
	v_ldexp_f32 v44, v44, v47
	v_cndmask_b32_e32 v44, 0, v44, vcc
	v_cmp_ngt_f32_e32 vcc, s2, v43
	s_nop 1
	v_cndmask_b32_e32 v43, v225, v44, vcc
	v_sub_f32_e32 v47, 1.0, v43
.LBB0_810:
	s_andn2_saveexec_b64 s[0:1], s[0:1]
	v_mul_f32_e32 v43, v45, v45
	v_fmamk_f32 v44, v43, 0xba1345e1, v220
	v_fmaak_f32 v44, v43, v44, 0xbcdac9b8
	v_fmaak_f32 v44, v43, v44, 0x3de703be
	v_fmaak_f32 v44, v43, v44, 0xbec09330
	v_fmaak_f32 v43, v43, v44, 0x3e0375d0
	v_fma_f32 v47, |v45|, v43, |v45|
	s_or_b64 exec, exec, s[0:1]
	v_cvt_f32_f16_sdwa v43, v171 dst_sel:DWORD dst_unused:UNUSED_PAD src0_sel:WORD_1
	v_mul_f32_e32 v21, 0x3f3504f3, v43
	v_cmp_nlt_f32_e64 s[0:1], |v21|, 1.0
	s_and_saveexec_b64 s[2:3], s[0:1]
	s_xor_b64 s[0:1], exec, s[2:3]
	s_cbranch_execz .LBB0_814
	v_fma_f32 v44, |v21|, s77, v224
	s_mov_b32 s2, 0x3b7cd369
	v_fma_f32 v44, |v21|, v44, s2
	s_mov_b32 s2, 0xbcc618b2
	v_fma_f32 v44, |v21|, v44, s2
	s_mov_b32 s2, 0x3dda74e4
	v_fma_f32 v44, |v21|, v44, s2
	s_mov_b32 s2, 0x3f228afd
	v_fma_f32 v44, |v21|, v44, s2
	s_mov_b32 s2, 0x3e03c728
	v_fma_f32 v44, |v21|, v44, s2
	v_fma_f32 v44, |v21|, v44, |v21|
	v_mul_f32_e32 v48, 0xbfb8aa3b, v44
	s_mov_b32 s2, 0xbfb8aa3b
	v_fma_f32 v49, v44, s2, -v48
	v_rndne_f32_e32 v50, v48
	v_fmac_f32_e32 v49, 0xb2a5705f, v44
	v_sub_f32_e32 v48, v48, v50
	v_add_f32_e32 v48, v48, v49
	v_cvt_i32_f32_e32 v49, v50
	v_exp_f32_e32 v48, v48
	s_mov_b32 s2, 0x42ce8ed0
	v_cmp_nlt_f32_e32 vcc, s2, v44
	s_mov_b32 s2, 0xc2b17218
	v_ldexp_f32 v48, v48, v49
	v_cndmask_b32_e32 v48, 0, v48, vcc
	v_cmp_ngt_f32_e32 vcc, s2, v44
	s_nop 1
	v_cndmask_b32_e32 v44, v225, v48, vcc
	v_sub_f32_e32 v44, 1.0, v44
.LBB0_814:
	s_andn2_saveexec_b64 s[0:1], s[0:1]
	v_mul_f32_e32 v44, v21, v21
	v_fmamk_f32 v48, v44, 0xba1345e1, v220
	v_fmaak_f32 v48, v44, v48, 0xbcdac9b8
	v_fmaak_f32 v48, v44, v48, 0x3de703be
	v_fmaak_f32 v48, v44, v48, 0xbec09330
	v_fmaak_f32 v44, v44, v48, 0x3e0375d0
	v_fma_f32 v44, |v21|, v44, |v21|
	s_or_b64 exec, exec, s[0:1]
	s_brev_b32 s2, -2
	v_bfi_b32 v45, s2, v47, v45
	v_mul_f32_e32 v46, 0.5, v46
	v_add_f32_e32 v45, 1.0, v45
	v_mul_f32_e32 v45, v46, v45
	v_add_f32_e32 v24, v34, v24
	v_mul_f32_e32 v24, v24, v45
	s_waitcnt vmcnt(13)
	v_cvt_f32_f16_e32 v45, v173
	v_bfi_b32 v35, s2, v41, v35
	v_mul_f32_e32 v0, 0.5, v0
	v_add_f32_e32 v35, 1.0, v35
	v_mul_f32_e32 v46, 0xbfb8aa3b, v45
	v_exp_f32_e32 v46, v46
	v_mul_f32_e32 v0, v0, v35
	v_add_f32_e32 v22, v34, v22
	v_mul_f32_e32 v0, v22, v0
	v_add_f32_e32 v46, 1.0, v46
	v_div_scale_f32 v47, s[0:1], v46, v46, v45
	v_rcp_f32_e32 v48, v47
	v_cvt_f32_f16_e32 v22, v172
	v_cvt_f32_f16_sdwa v18, v172 dst_sel:DWORD dst_unused:UNUSED_PAD src0_sel:WORD_1
	v_mov_b32_e32 v210, v23
	v_fma_f32 v49, -v47, v48, 1.0
	v_fmac_f32_e32 v48, v49, v48
	v_div_scale_f32 v49, vcc, v45, v46, v45
	v_mul_f32_e32 v35, 0xbfb8aa3b, v22
	v_mul_f32_e32 v50, v49, v48
	v_exp_f32_e32 v35, v35
	v_fma_f32 v51, -v47, v50, v49
	v_fmac_f32_e32 v50, v51, v48
	v_fma_f32 v47, -v47, v50, v49
	v_div_fmas_f32 v47, v47, v48, v50
	v_add_f32_e32 v35, 1.0, v35
	v_div_fixup_f32 v45, v47, v46, v45
	v_div_scale_f32 v41, s[0:1], v35, v35, v22
	v_mul_f32_e32 v24, v45, v24
	v_rcp_f32_e32 v45, v41
	v_mul_f32_e32 v20, 0.5, v20
	v_cvt_f32_f16_sdwa v19, v173 dst_sel:DWORD dst_unused:UNUSED_PAD src0_sel:WORD_1
	v_fma_f32 v46, -v41, v45, 1.0
	v_fmac_f32_e32 v45, v46, v45
	v_div_scale_f32 v46, vcc, v22, v35, v22
	v_mul_f32_e32 v47, v46, v45
	v_fma_f32 v48, -v41, v47, v46
	v_fmac_f32_e32 v47, v48, v45
	v_fma_f32 v41, -v41, v47, v46
	v_div_fmas_f32 v41, v41, v45, v47
	v_div_fixup_f32 v22, v41, v35, v22
	v_bfi_b32 v35, s2, v42, v40
	v_mul_f32_e32 v0, v22, v0
	v_pk_add_f32 v[22:23], v[34:35], v[210:211]
	v_mov_b32_e32 v210, v25
	v_mul_f32_e32 v20, v20, v23
	v_mul_f32_e32 v20, v22, v20
	v_mul_f32_e32 v22, 0xbfb8aa3b, v18
	v_exp_f32_e32 v22, v22
	s_nop 0
	v_add_f32_e32 v22, 1.0, v22
	v_div_scale_f32 v23, s[0:1], v22, v22, v18
	v_rcp_f32_e32 v35, v23
	s_nop 0
	v_fma_f32 v40, -v23, v35, 1.0
	v_fmac_f32_e32 v35, v40, v35
	v_div_scale_f32 v40, vcc, v18, v22, v18
	v_mul_f32_e32 v41, v40, v35
	v_fma_f32 v42, -v23, v41, v40
	v_fmac_f32_e32 v41, v42, v35
	v_fma_f32 v23, -v23, v41, v40
	v_div_fmas_f32 v23, v23, v35, v41
	v_div_fixup_f32 v18, v23, v22, v18
	v_mul_f32_e32 v18, v18, v20
	v_bfi_b32 v35, s2, v44, v21
	v_cvt_pk_f16_f32 v18, v0, v18
	v_mul_f32_e32 v0, 0.5, v43
	v_pk_add_f32 v[20:21], v[34:35], v[210:211]
	s_nop 0
	v_mul_f32_e32 v0, v0, v21
	v_mul_f32_e32 v0, v20, v0
	v_mul_f32_e32 v20, 0xbfb8aa3b, v19
	v_exp_f32_e32 v20, v20
	s_nop 0
	v_add_f32_e32 v20, 1.0, v20
	v_div_scale_f32 v21, s[0:1], v20, v20, v19
	v_rcp_f32_e32 v22, v21
	s_nop 0
	v_fma_f32 v23, -v21, v22, 1.0
	v_fmac_f32_e32 v22, v23, v22
	v_div_scale_f32 v23, vcc, v19, v20, v19
	v_mul_f32_e32 v25, v23, v22
	v_fma_f32 v35, -v21, v25, v23
	v_fmac_f32_e32 v25, v35, v22
	v_fma_f32 v21, -v21, v25, v23
	v_div_fmas_f32 v21, v21, v22, v25
	v_div_fixup_f32 v19, v21, v20, v19
	v_mul_f32_e32 v0, v19, v0
	v_cvt_pk_f16_f32 v19, v24, v0
	global_store_dwordx2 v[36:37], v[18:19], off offset:16
	s_nop 0
	s_waitcnt vmcnt(13)
	v_cvt_f32_f16_e32 v0, v174
	v_mul_f32_e32 v22, 0x3f3504f3, v0
	v_cmp_nlt_f32_e64 s[0:1], |v22|, 1.0
	s_and_saveexec_b64 s[2:3], s[0:1]
	s_xor_b64 s[0:1], exec, s[2:3]
	s_cbranch_execz .LBB0_818
; DI unsigned pk2(float a, float b) { f2_t v = {a, b}; bf2_t r = __builtin_convertvector(v, bf2_t); return __builtin_bit_cast(unsigned, r); }
; DI float bflo(unsigned u) { return (float)__builtin_bit_cast(bf2_t, u)[0]; }
; DI float bfhi(unsigned u) { return (float)__builtin_bit_cast(bf2_t, u)[1]; }
; DI float siluf_(float x) { return x / (1.f + __expf(-x)); }
; DI float geluf_(float x) { return 0.5f * x * (1.f + erff(x * 0.70710678118654752f)); }
; DI void sg_item(const Params& p, int l, int item, char* lds, int dry) {
;     ...
;     for (int a4 = 0; a4 < 4; ++a4) {
;       const int d = db * 32 + 8 * a4 + 4 * h;
;       const uint2 uv = *(const uint2*)(zr + UD + g * 64 + d);
;     ...
;       o.x = pk2(geluf_(bflo(uv.x)) * (acc[db][4 * a4] + bsv) * siluf_(bflo(gv.x)),
;                 geluf_(bfhi(uv.x)) * (acc[db][4 * a4 + 1] + bsv) * siluf_(bfhi(gv.x)));
;       o.y = pk2(geluf_(bflo(uv.y)) * (acc[db][4 * a4 + 2] + bsv) * siluf_(bflo(gv.y)),
;                 geluf_(bfhi(uv.y)) * (acc[db][4 * a4 + 3] + bsv) * siluf_(bfhi(gv.y)));
	v_fma_f32 v23, |v22|, s77, v224
	s_mov_b32 s2, 0x3b7cd369
	v_fma_f32 v23, |v22|, v23, s2
	s_mov_b32 s2, 0xbcc618b2
	v_fma_f32 v23, |v22|, v23, s2
	s_mov_b32 s2, 0x3dda74e4
	v_fma_f32 v23, |v22|, v23, s2
	s_mov_b32 s2, 0x3f228afd
	v_fma_f32 v23, |v22|, v23, s2
	s_mov_b32 s2, 0x3e03c728
	v_fma_f32 v23, |v22|, v23, s2
	v_fma_f32 v23, |v22|, v23, |v22|
	v_mul_f32_e32 v24, 0xbfb8aa3b, v23
	s_mov_b32 s2, 0xbfb8aa3b
	v_fma_f32 v25, v23, s2, -v24
	v_rndne_f32_e32 v35, v24
	v_fmac_f32_e32 v25, 0xb2a5705f, v23
	v_sub_f32_e32 v24, v24, v35
	v_add_f32_e32 v24, v24, v25
	v_cvt_i32_f32_e32 v25, v35
	v_exp_f32_e32 v24, v24
	s_mov_b32 s2, 0x42ce8ed0
	v_cmp_nlt_f32_e32 vcc, s2, v23
	s_mov_b32 s2, 0xc2b17218
	v_ldexp_f32 v24, v24, v25
	v_cndmask_b32_e32 v24, 0, v24, vcc
	v_cmp_ngt_f32_e32 vcc, s2, v23
	s_nop 1
	v_cndmask_b32_e32 v23, v225, v24, vcc
	v_sub_f32_e32 v24, 1.0, v23
.LBB0_818:
	s_andn2_saveexec_b64 s[0:1], s[0:1]
	v_mul_f32_e32 v23, v22, v22
	v_fmamk_f32 v24, v23, 0xba1345e1, v220
	v_fmaak_f32 v24, v23, v24, 0xbcdac9b8
	v_fmaak_f32 v24, v23, v24, 0x3de703be
	v_fmaak_f32 v24, v23, v24, 0xbec09330
	v_fmaak_f32 v23, v23, v24, 0x3e0375d0
	v_fma_f32 v24, |v22|, v23, |v22|
	s_or_b64 exec, exec, s[0:1]
	v_cvt_f32_f16_sdwa v20, v174 dst_sel:DWORD dst_unused:UNUSED_PAD src0_sel:WORD_1
	v_mul_f32_e32 v23, 0x3f3504f3, v20
	v_cmp_nlt_f32_e64 s[0:1], |v23|, 1.0
	s_and_saveexec_b64 s[2:3], s[0:1]
	s_xor_b64 s[0:1], exec, s[2:3]
	s_cbranch_execz .LBB0_822
	v_fma_f32 v25, |v23|, s77, v224
	s_mov_b32 s2, 0x3b7cd369
	v_fma_f32 v25, |v23|, v25, s2
	s_mov_b32 s2, 0xbcc618b2
	v_fma_f32 v25, |v23|, v25, s2
	s_mov_b32 s2, 0x3dda74e4
	v_fma_f32 v25, |v23|, v25, s2
	s_mov_b32 s2, 0x3f228afd
	v_fma_f32 v25, |v23|, v25, s2
	s_mov_b32 s2, 0x3e03c728
	v_fma_f32 v25, |v23|, v25, s2
	v_fma_f32 v25, |v23|, v25, |v23|
	v_mul_f32_e32 v35, 0xbfb8aa3b, v25
	s_mov_b32 s2, 0xbfb8aa3b
	v_fma_f32 v40, v25, s2, -v35
	v_rndne_f32_e32 v41, v35
	v_fmac_f32_e32 v40, 0xb2a5705f, v25
	v_sub_f32_e32 v35, v35, v41
	v_add_f32_e32 v35, v35, v40
	v_cvt_i32_f32_e32 v40, v41
	v_exp_f32_e32 v35, v35
	s_mov_b32 s2, 0x42ce8ed0
	v_cmp_nlt_f32_e32 vcc, s2, v25
	s_mov_b32 s2, 0xc2b17218
	v_ldexp_f32 v35, v35, v40
	v_cndmask_b32_e32 v35, 0, v35, vcc
	v_cmp_ngt_f32_e32 vcc, s2, v25
	s_nop 1
	v_cndmask_b32_e32 v25, v225, v35, vcc
	v_sub_f32_e32 v25, 1.0, v25
.LBB0_822:
	s_andn2_saveexec_b64 s[0:1], s[0:1]
	v_mul_f32_e32 v25, v23, v23
	v_fmamk_f32 v35, v25, 0xba1345e1, v220
	v_fmaak_f32 v35, v25, v35, 0xbcdac9b8
	v_fmaak_f32 v35, v25, v35, 0x3de703be
	v_fmaak_f32 v35, v25, v35, 0xbec09330
	v_fmaak_f32 v25, v25, v35, 0x3e0375d0
	v_fma_f32 v25, |v23|, v25, |v23|
	s_or_b64 exec, exec, s[0:1]
	v_cvt_f32_f16_e32 v42, v175
	v_mul_f32_e32 v35, 0x3f3504f3, v42
	v_cmp_nlt_f32_e64 s[0:1], |v35|, 1.0
	s_and_saveexec_b64 s[2:3], s[0:1]
	s_xor_b64 s[0:1], exec, s[2:3]
	s_cbranch_execz .LBB0_826
	v_fma_f32 v40, |v35|, s77, v224
	s_mov_b32 s2, 0x3b7cd369
	v_fma_f32 v40, |v35|, v40, s2
	s_mov_b32 s2, 0xbcc618b2
	v_fma_f32 v40, |v35|, v40, s2
	s_mov_b32 s2, 0x3dda74e4
	v_fma_f32 v40, |v35|, v40, s2
	s_mov_b32 s2, 0x3f228afd
	v_fma_f32 v40, |v35|, v40, s2
	s_mov_b32 s2, 0x3e03c728
	v_fma_f32 v40, |v35|, v40, s2
	v_fma_f32 v40, |v35|, v40, |v35|
	v_mul_f32_e32 v41, 0xbfb8aa3b, v40
	s_mov_b32 s2, 0xbfb8aa3b
	v_fma_f32 v43, v40, s2, -v41
	v_rndne_f32_e32 v44, v41
	v_fmac_f32_e32 v43, 0xb2a5705f, v40
	v_sub_f32_e32 v41, v41, v44
	v_add_f32_e32 v41, v41, v43
	v_cvt_i32_f32_e32 v43, v44
	v_exp_f32_e32 v41, v41
	s_mov_b32 s2, 0x42ce8ed0
	v_cmp_nlt_f32_e32 vcc, s2, v40
	s_mov_b32 s2, 0xc2b17218
	v_ldexp_f32 v41, v41, v43
	v_cndmask_b32_e32 v41, 0, v41, vcc
	v_cmp_ngt_f32_e32 vcc, s2, v40
	s_nop 1
	v_cndmask_b32_e32 v40, v225, v41, vcc
	v_sub_f32_e32 v43, 1.0, v40
.LBB0_826:
	s_andn2_saveexec_b64 s[0:1], s[0:1]
	v_mul_f32_e32 v40, v35, v35
	v_fmamk_f32 v41, v40, 0xba1345e1, v220
	v_fmaak_f32 v41, v40, v41, 0xbcdac9b8
	v_fmaak_f32 v41, v40, v41, 0x3de703be
	v_fmaak_f32 v41, v40, v41, 0xbec09330
	v_fmaak_f32 v40, v40, v41, 0x3e0375d0
	v_fma_f32 v43, |v35|, v40, |v35|
	s_or_b64 exec, exec, s[0:1]
	v_cvt_f32_f16_sdwa v40, v175 dst_sel:DWORD dst_unused:UNUSED_PAD src0_sel:WORD_1
	v_mul_f32_e32 v21, 0x3f3504f3, v40
	v_cmp_nlt_f32_e64 s[0:1], |v21|, 1.0
	s_and_saveexec_b64 s[2:3], s[0:1]
	s_xor_b64 s[0:1], exec, s[2:3]
	s_cbranch_execz .LBB0_830
	v_fma_f32 v41, |v21|, s77, v224
	s_mov_b32 s2, 0x3b7cd369
	v_fma_f32 v41, |v21|, v41, s2
	s_mov_b32 s2, 0xbcc618b2
	v_fma_f32 v41, |v21|, v41, s2
	s_mov_b32 s2, 0x3dda74e4
	v_fma_f32 v41, |v21|, v41, s2
	s_mov_b32 s2, 0x3f228afd
	v_fma_f32 v41, |v21|, v41, s2
	s_mov_b32 s2, 0x3e03c728
	v_fma_f32 v41, |v21|, v41, s2
	v_fma_f32 v41, |v21|, v41, |v21|
	v_mul_f32_e32 v44, 0xbfb8aa3b, v41
	s_mov_b32 s2, 0xbfb8aa3b
	v_fma_f32 v45, v41, s2, -v44
	v_rndne_f32_e32 v46, v44
	v_fmac_f32_e32 v45, 0xb2a5705f, v41
	v_sub_f32_e32 v44, v44, v46
	v_add_f32_e32 v44, v44, v45
	v_cvt_i32_f32_e32 v45, v46
	v_exp_f32_e32 v44, v44
	s_mov_b32 s2, 0x42ce8ed0
	v_cmp_nlt_f32_e32 vcc, s2, v41
	s_mov_b32 s2, 0xc2b17218
	v_ldexp_f32 v44, v44, v45
	v_cndmask_b32_e32 v44, 0, v44, vcc
	v_cmp_ngt_f32_e32 vcc, s2, v41
	s_nop 1
	v_cndmask_b32_e32 v41, v225, v44, vcc
	v_sub_f32_e32 v41, 1.0, v41
; DI unsigned pk2(float a, float b) { f2_t v = {a, b}; bf2_t r = __builtin_convertvector(v, bf2_t); return __builtin_bit_cast(unsigned, r); }
; DI float bflo(unsigned u) { return (float)__builtin_bit_cast(bf2_t, u)[0]; }
; DI float bfhi(unsigned u) { return (float)__builtin_bit_cast(bf2_t, u)[1]; }
; DI float siluf_(float x) { return x / (1.f + __expf(-x)); }
; DI float geluf_(float x) { return 0.5f * x * (1.f + erff(x * 0.70710678118654752f)); }
; DI void sg_item(const Params& p, int l, int item, char* lds, int dry) {
;     ...
;     for (int a4 = 0; a4 < 4; ++a4) {
;       const int d = db * 32 + 8 * a4 + 4 * h;
;       const uint2 uv = *(const uint2*)(zr + UD + g * 64 + d);
;       uint2* gp = (uint2*)(zr + GD + g * 64 + d);
;       const uint2 gv = *gp;
;       uint2 o;
;       o.x = pk2(geluf_(bflo(uv.x)) * (acc[db][4 * a4] + bsv) * siluf_(bflo(gv.x)),
;                 geluf_(bfhi(uv.x)) * (acc[db][4 * a4 + 1] + bsv) * siluf_(bfhi(gv.x)));
;       o.y = pk2(geluf_(bflo(uv.y)) * (acc[db][4 * a4 + 2] + bsv) * siluf_(bflo(gv.y)),
;                 geluf_(bfhi(uv.y)) * (acc[db][4 * a4 + 3] + bsv) * siluf_(bfhi(gv.y)));
;       if (dry) gp = (uint2*)(p.blkscr + (size_t)blockIdx.x * 8 * 256 + tid + ((db * 4 + a4) >> 1) * 256) + (a4 & 1);
;       *gp = o;
.LBB0_830:
	s_andn2_saveexec_b64 s[0:1], s[0:1]
	v_mul_f32_e32 v41, v21, v21
	v_fmamk_f32 v44, v41, 0xba1345e1, v220
	v_fmaak_f32 v44, v41, v44, 0xbcdac9b8
	v_fmaak_f32 v44, v41, v44, 0x3de703be
	v_fmaak_f32 v44, v41, v44, 0xbec09330
	v_fmaak_f32 v41, v41, v44, 0x3e0375d0
	v_fma_f32 v41, |v21|, v41, |v21|
	s_or_b64 exec, exec, s[0:1]
	s_brev_b32 s2, -2
	v_bfi_b32 v35, s2, v43, v35
	v_mul_f32_e32 v42, 0.5, v42
	v_add_f32_e32 v35, 1.0, v35
	v_mul_f32_e32 v35, v42, v35
	v_add_f32_e32 v28, v34, v28
	v_mul_f32_e32 v28, v28, v35
	s_waitcnt vmcnt(12)
	v_cvt_f32_f16_e32 v35, v177
	v_bfi_b32 v22, s2, v24, v22
	v_mul_f32_e32 v0, 0.5, v0
	v_add_f32_e32 v22, 1.0, v22
	v_mul_f32_e32 v42, 0xbfb8aa3b, v35
	v_exp_f32_e32 v42, v42
	v_mul_f32_e32 v0, v0, v22
	v_add_f32_e32 v22, v34, v26
	v_mul_f32_e32 v0, v22, v0
	v_add_f32_e32 v42, 1.0, v42
	v_div_scale_f32 v43, s[0:1], v42, v42, v35
	v_rcp_f32_e32 v44, v43
	v_cvt_f32_f16_e32 v22, v176
	v_cvt_f32_f16_sdwa v18, v176 dst_sel:DWORD dst_unused:UNUSED_PAD src0_sel:WORD_1
	v_mov_b32_e32 v210, v27
	v_fma_f32 v45, -v43, v44, 1.0
	v_fmac_f32_e32 v44, v45, v44
	v_div_scale_f32 v45, vcc, v35, v42, v35
	v_mul_f32_e32 v24, 0xbfb8aa3b, v22
	v_mul_f32_e32 v46, v45, v44
	v_exp_f32_e32 v24, v24
	v_fma_f32 v47, -v43, v46, v45
	v_fmac_f32_e32 v46, v47, v44
	v_fma_f32 v43, -v43, v46, v45
	v_div_fmas_f32 v43, v43, v44, v46
	v_add_f32_e32 v24, 1.0, v24
	v_div_fixup_f32 v35, v43, v42, v35
	v_div_scale_f32 v26, s[0:1], v24, v24, v22
	v_mul_f32_e32 v28, v35, v28
	v_rcp_f32_e32 v35, v26
	v_mul_f32_e32 v20, 0.5, v20
	v_cvt_f32_f16_sdwa v19, v177 dst_sel:DWORD dst_unused:UNUSED_PAD src0_sel:WORD_1
	v_fma_f32 v42, -v26, v35, 1.0
	v_fmac_f32_e32 v35, v42, v35
	v_div_scale_f32 v42, vcc, v22, v24, v22
	v_mul_f32_e32 v43, v42, v35
	v_fma_f32 v44, -v26, v43, v42
	v_fmac_f32_e32 v43, v44, v35
	v_fma_f32 v26, -v26, v43, v42
	v_div_fmas_f32 v26, v26, v35, v43
	v_div_fixup_f32 v22, v26, v24, v22
	v_bfi_b32 v35, s2, v25, v23
	v_mul_f32_e32 v0, v22, v0
	v_pk_add_f32 v[22:23], v[34:35], v[210:211]
	v_bfi_b32 v35, s2, v41, v21
	v_mul_f32_e32 v20, v20, v23
	v_mul_f32_e32 v20, v22, v20
	v_mul_f32_e32 v22, 0xbfb8aa3b, v18
	v_exp_f32_e32 v22, v22
	v_mov_b32_e32 v210, v29
	v_add_f32_e32 v22, 1.0, v22
	v_div_scale_f32 v23, s[0:1], v22, v22, v18
	v_rcp_f32_e32 v24, v23
	s_nop 0
	v_fma_f32 v25, -v23, v24, 1.0
	v_fmac_f32_e32 v24, v25, v24
	v_div_scale_f32 v25, vcc, v18, v22, v18
	v_mul_f32_e32 v26, v25, v24
	v_fma_f32 v27, -v23, v26, v25
	v_fmac_f32_e32 v26, v27, v24
	v_fma_f32 v23, -v23, v26, v25
	v_div_fmas_f32 v23, v23, v24, v26
	v_div_fixup_f32 v18, v23, v22, v18
	v_mul_f32_e32 v18, v18, v20
	v_cvt_pk_f16_f32 v18, v0, v18
	v_mul_f32_e32 v0, 0.5, v40
	v_pk_add_f32 v[20:21], v[34:35], v[210:211]
	s_nop 0
	v_mul_f32_e32 v0, v0, v21
	v_mul_f32_e32 v0, v20, v0
	v_mul_f32_e32 v20, 0xbfb8aa3b, v19
	v_exp_f32_e32 v20, v20
	s_nop 0
	v_add_f32_e32 v20, 1.0, v20
	v_div_scale_f32 v21, s[0:1], v20, v20, v19
	v_rcp_f32_e32 v22, v21
	s_nop 0
	v_fma_f32 v23, -v21, v22, 1.0
	v_fmac_f32_e32 v22, v23, v22
	v_div_scale_f32 v23, vcc, v19, v20, v19
	v_mul_f32_e32 v24, v23, v22
	v_fma_f32 v25, -v21, v24, v23
	v_fmac_f32_e32 v24, v25, v22
	v_fma_f32 v21, -v21, v24, v23
	v_div_fmas_f32 v21, v21, v22, v24
	v_div_fixup_f32 v19, v21, v20, v19
	v_mul_f32_e32 v0, v19, v0
	v_cvt_pk_f16_f32 v19, v28, v0
	global_store_dwordx2 v[36:37], v[18:19], off offset:32
	s_nop 0
	s_waitcnt vmcnt(12)
	v_cvt_f32_f16_e32 v0, v178
	v_mul_f32_e32 v22, 0x3f3504f3, v0
	v_cmp_nlt_f32_e64 s[0:1], |v22|, 1.0
	s_and_saveexec_b64 s[2:3], s[0:1]
	s_xor_b64 s[0:1], exec, s[2:3]
	s_cbranch_execz .LBB0_834
	v_fma_f32 v23, |v22|, s77, v224
	s_mov_b32 s2, 0x3b7cd369
	v_fma_f32 v23, |v22|, v23, s2
	s_mov_b32 s2, 0xbcc618b2
	v_fma_f32 v23, |v22|, v23, s2
	s_mov_b32 s2, 0x3dda74e4
	v_fma_f32 v23, |v22|, v23, s2
	s_mov_b32 s2, 0x3f228afd
	v_fma_f32 v23, |v22|, v23, s2
	s_mov_b32 s2, 0x3e03c728
	v_fma_f32 v23, |v22|, v23, s2
	v_fma_f32 v23, |v22|, v23, |v22|
	v_mul_f32_e32 v24, 0xbfb8aa3b, v23
	s_mov_b32 s2, 0xbfb8aa3b
	v_fma_f32 v25, v23, s2, -v24
	v_rndne_f32_e32 v26, v24
	v_fmac_f32_e32 v25, 0xb2a5705f, v23
	v_sub_f32_e32 v24, v24, v26
	v_add_f32_e32 v24, v24, v25
	v_cvt_i32_f32_e32 v25, v26
	v_exp_f32_e32 v24, v24
	s_mov_b32 s2, 0x42ce8ed0
	v_cmp_nlt_f32_e32 vcc, s2, v23
	s_mov_b32 s2, 0xc2b17218
	v_ldexp_f32 v24, v24, v25
	v_cndmask_b32_e32 v24, 0, v24, vcc
	v_cmp_ngt_f32_e32 vcc, s2, v23
	s_nop 1
	v_cndmask_b32_e32 v23, v225, v24, vcc
	v_sub_f32_e32 v24, 1.0, v23
.LBB0_834:
	s_andn2_saveexec_b64 s[0:1], s[0:1]
	v_mul_f32_e32 v23, v22, v22
	v_fmamk_f32 v24, v23, 0xba1345e1, v220
	v_fmaak_f32 v24, v23, v24, 0xbcdac9b8
	v_fmaak_f32 v24, v23, v24, 0x3de703be
	v_fmaak_f32 v24, v23, v24, 0xbec09330
	v_fmaak_f32 v23, v23, v24, 0x3e0375d0
	v_fma_f32 v24, |v22|, v23, |v22|
	s_or_b64 exec, exec, s[0:1]
	v_cvt_f32_f16_sdwa v20, v178 dst_sel:DWORD dst_unused:UNUSED_PAD src0_sel:WORD_1
	v_mul_f32_e32 v23, 0x3f3504f3, v20
	v_cmp_nlt_f32_e64 s[0:1], |v23|, 1.0
	s_and_saveexec_b64 s[2:3], s[0:1]
	s_xor_b64 s[0:1], exec, s[2:3]
	s_cbranch_execz .LBB0_838
	v_fma_f32 v25, |v23|, s77, v224
	s_mov_b32 s2, 0x3b7cd369
	v_fma_f32 v25, |v23|, v25, s2
	s_mov_b32 s2, 0xbcc618b2
	v_fma_f32 v25, |v23|, v25, s2
	s_mov_b32 s2, 0x3dda74e4
	v_fma_f32 v25, |v23|, v25, s2
	s_mov_b32 s2, 0x3f228afd
	v_fma_f32 v25, |v23|, v25, s2
	s_mov_b32 s2, 0x3e03c728
	v_fma_f32 v25, |v23|, v25, s2
	v_fma_f32 v25, |v23|, v25, |v23|
	v_mul_f32_e32 v26, 0xbfb8aa3b, v25
	s_mov_b32 s2, 0xbfb8aa3b
	v_fma_f32 v27, v25, s2, -v26
	v_rndne_f32_e32 v28, v26
	v_fmac_f32_e32 v27, 0xb2a5705f, v25
	v_sub_f32_e32 v26, v26, v28
	v_add_f32_e32 v26, v26, v27
	v_cvt_i32_f32_e32 v27, v28
	v_exp_f32_e32 v26, v26
	s_mov_b32 s2, 0x42ce8ed0
	v_cmp_nlt_f32_e32 vcc, s2, v25
	s_mov_b32 s2, 0xc2b17218
	v_ldexp_f32 v26, v26, v27
	v_cndmask_b32_e32 v26, 0, v26, vcc
	v_cmp_ngt_f32_e32 vcc, s2, v25
	s_nop 1
	v_cndmask_b32_e32 v25, v225, v26, vcc
	v_sub_f32_e32 v25, 1.0, v25
; DI unsigned pk2(float a, float b) { f2_t v = {a, b}; bf2_t r = __builtin_convertvector(v, bf2_t); return __builtin_bit_cast(unsigned, r); }
; DI float bflo(unsigned u) { return (float)__builtin_bit_cast(bf2_t, u)[0]; }
; DI float bfhi(unsigned u) { return (float)__builtin_bit_cast(bf2_t, u)[1]; }
; DI float siluf_(float x) { return x / (1.f + __expf(-x)); }
; DI float geluf_(float x) { return 0.5f * x * (1.f + erff(x * 0.70710678118654752f)); }
; DI void sg_item(const Params& p, int l, int item, char* lds, int dry) {
;     ...
;     for (int a4 = 0; a4 < 4; ++a4) {
;       const int d = db * 32 + 8 * a4 + 4 * h;
;       const uint2 uv = *(const uint2*)(zr + UD + g * 64 + d);
;       uint2* gp = (uint2*)(zr + GD + g * 64 + d);
;       const uint2 gv = *gp;
;       uint2 o;
;       o.x = pk2(geluf_(bflo(uv.x)) * (acc[db][4 * a4] + bsv) * siluf_(bflo(gv.x)),
;                 geluf_(bfhi(uv.x)) * (acc[db][4 * a4 + 1] + bsv) * siluf_(bfhi(gv.x)));
;       o.y = pk2(geluf_(bflo(uv.y)) * (acc[db][4 * a4 + 2] + bsv) * siluf_(bflo(gv.y)),
;                 geluf_(bfhi(uv.y)) * (acc[db][4 * a4 + 3] + bsv) * siluf_(bfhi(gv.y)));
;       if (dry) gp = (uint2*)(p.blkscr + (size_t)blockIdx.x * 8 * 256 + tid + ((db * 4 + a4) >> 1) * 256) + (a4 & 1);
;       *gp = o;
.LBB0_838:
	s_andn2_saveexec_b64 s[0:1], s[0:1]
	v_mul_f32_e32 v25, v23, v23
	v_fmamk_f32 v26, v25, 0xba1345e1, v220
	v_fmaak_f32 v26, v25, v26, 0xbcdac9b8
	v_fmaak_f32 v26, v25, v26, 0x3de703be
	v_fmaak_f32 v26, v25, v26, 0xbec09330
	v_fmaak_f32 v25, v25, v26, 0x3e0375d0
	v_fma_f32 v25, |v23|, v25, |v23|
	s_or_b64 exec, exec, s[0:1]
	v_cvt_f32_f16_e32 v29, v179
	v_mul_f32_e32 v28, 0x3f3504f3, v29
	v_cmp_nlt_f32_e64 s[0:1], |v28|, 1.0
	s_and_saveexec_b64 s[2:3], s[0:1]
	s_xor_b64 s[0:1], exec, s[2:3]
	s_cbranch_execz .LBB0_842
	v_fma_f32 v26, |v28|, s77, v224
	s_mov_b32 s2, 0x3b7cd369
	v_fma_f32 v26, |v28|, v26, s2
	s_mov_b32 s2, 0xbcc618b2
	v_fma_f32 v26, |v28|, v26, s2
	s_mov_b32 s2, 0x3dda74e4
	v_fma_f32 v26, |v28|, v26, s2
	s_mov_b32 s2, 0x3f228afd
	v_fma_f32 v26, |v28|, v26, s2
	s_mov_b32 s2, 0x3e03c728
	v_fma_f32 v26, |v28|, v26, s2
	v_fma_f32 v26, |v28|, v26, |v28|
	v_mul_f32_e32 v27, 0xbfb8aa3b, v26
	s_mov_b32 s2, 0xbfb8aa3b
	v_fma_f32 v35, v26, s2, -v27
	v_rndne_f32_e32 v40, v27
	v_fmac_f32_e32 v35, 0xb2a5705f, v26
	v_sub_f32_e32 v27, v27, v40
	v_add_f32_e32 v27, v27, v35
	v_cvt_i32_f32_e32 v35, v40
	v_exp_f32_e32 v27, v27
	s_mov_b32 s2, 0x42ce8ed0
	v_cmp_nlt_f32_e32 vcc, s2, v26
	s_mov_b32 s2, 0xc2b17218
	v_ldexp_f32 v27, v27, v35
	v_cndmask_b32_e32 v27, 0, v27, vcc
	v_cmp_ngt_f32_e32 vcc, s2, v26
	s_nop 1
	v_cndmask_b32_e32 v26, v225, v27, vcc
	v_sub_f32_e32 v35, 1.0, v26
.LBB0_842:
	s_andn2_saveexec_b64 s[0:1], s[0:1]
	v_mul_f32_e32 v26, v28, v28
	v_fmamk_f32 v27, v26, 0xba1345e1, v220
	v_fmaak_f32 v27, v26, v27, 0xbcdac9b8
	v_fmaak_f32 v27, v26, v27, 0x3de703be
	v_fmaak_f32 v27, v26, v27, 0xbec09330
	v_fmaak_f32 v26, v26, v27, 0x3e0375d0
	v_fma_f32 v35, |v28|, v26, |v28|
	s_or_b64 exec, exec, s[0:1]
	v_cvt_f32_f16_sdwa v26, v179 dst_sel:DWORD dst_unused:UNUSED_PAD src0_sel:WORD_1
	v_mul_f32_e32 v21, 0x3f3504f3, v26
	v_cmp_nlt_f32_e64 s[0:1], |v21|, 1.0
	s_and_saveexec_b64 s[2:3], s[0:1]
	s_xor_b64 s[0:1], exec, s[2:3]
	s_cbranch_execz .LBB0_846
	v_fma_f32 v27, |v21|, s77, v224
	s_mov_b32 s2, 0x3b7cd369
	v_fma_f32 v27, |v21|, v27, s2
	s_mov_b32 s2, 0xbcc618b2
	v_fma_f32 v27, |v21|, v27, s2
	s_mov_b32 s2, 0x3dda74e4
	v_fma_f32 v27, |v21|, v27, s2
	s_mov_b32 s2, 0x3f228afd
	v_fma_f32 v27, |v21|, v27, s2
	s_mov_b32 s2, 0x3e03c728
	v_fma_f32 v27, |v21|, v27, s2
	v_fma_f32 v27, |v21|, v27, |v21|
	v_mul_f32_e32 v40, 0xbfb8aa3b, v27
	s_mov_b32 s2, 0xbfb8aa3b
	v_fma_f32 v41, v27, s2, -v40
	v_rndne_f32_e32 v42, v40
	v_fmac_f32_e32 v41, 0xb2a5705f, v27
	v_sub_f32_e32 v40, v40, v42
	v_add_f32_e32 v40, v40, v41
	v_cvt_i32_f32_e32 v41, v42
	v_exp_f32_e32 v40, v40
	s_mov_b32 s2, 0x42ce8ed0
	v_cmp_nlt_f32_e32 vcc, s2, v27
	s_mov_b32 s2, 0xc2b17218
	v_ldexp_f32 v40, v40, v41
	v_cndmask_b32_e32 v40, 0, v40, vcc
	v_cmp_ngt_f32_e32 vcc, s2, v27
	s_nop 1
	v_cndmask_b32_e32 v27, v225, v40, vcc
	v_sub_f32_e32 v27, 1.0, v27
.LBB0_846:
	s_andn2_saveexec_b64 s[0:1], s[0:1]
	v_mul_f32_e32 v27, v21, v21
	v_fmamk_f32 v40, v27, 0xba1345e1, v220
	v_fmaak_f32 v40, v27, v40, 0xbcdac9b8
	v_fmaak_f32 v40, v27, v40, 0x3de703be
	v_fmaak_f32 v40, v27, v40, 0xbec09330
	v_fmaak_f32 v27, v27, v40, 0x3e0375d0
	v_fma_f32 v27, |v21|, v27, |v21|
	s_or_b64 exec, exec, s[0:1]
	s_brev_b32 s2, -2
	v_bfi_b32 v28, s2, v35, v28
	v_mul_f32_e32 v29, 0.5, v29
	v_add_f32_e32 v28, 1.0, v28
	v_mul_f32_e32 v28, v29, v28
	v_add_f32_e32 v29, v34, v32
	v_mul_f32_e32 v28, v29, v28
	s_waitcnt vmcnt(11)
	v_cvt_f32_f16_e32 v29, v181
	v_bfi_b32 v22, s2, v24, v22
	v_mul_f32_e32 v0, 0.5, v0
	v_add_f32_e32 v22, 1.0, v22
	v_mul_f32_e32 v32, 0xbfb8aa3b, v29
	v_exp_f32_e32 v32, v32
	v_mul_f32_e32 v0, v0, v22
	v_add_f32_e32 v22, v34, v30
	v_mul_f32_e32 v0, v22, v0
	v_add_f32_e32 v32, 1.0, v32
	v_div_scale_f32 v35, s[0:1], v32, v32, v29
	v_rcp_f32_e32 v40, v35
	v_cvt_f32_f16_e32 v22, v180
	v_cvt_f32_f16_sdwa v18, v180 dst_sel:DWORD dst_unused:UNUSED_PAD src0_sel:WORD_1
	v_mov_b32_e32 v210, v31
	v_fma_f32 v41, -v35, v40, 1.0
	v_fmac_f32_e32 v40, v41, v40
	v_div_scale_f32 v41, vcc, v29, v32, v29
	v_mul_f32_e32 v42, v41, v40
	v_mul_f32_e32 v24, 0xbfb8aa3b, v22
	v_fma_f32 v43, -v35, v42, v41
	v_exp_f32_e32 v24, v24
	v_fmac_f32_e32 v42, v43, v40
	v_fma_f32 v35, -v35, v42, v41
	v_div_fmas_f32 v35, v35, v40, v42
	v_div_fixup_f32 v29, v35, v32, v29
	v_add_f32_e32 v24, 1.0, v24
	v_mul_f32_e32 v28, v29, v28
	v_div_scale_f32 v29, s[0:1], v24, v24, v22
	v_rcp_f32_e32 v30, v29
	v_mul_f32_e32 v20, 0.5, v20
	v_cvt_f32_f16_sdwa v19, v181 dst_sel:DWORD dst_unused:UNUSED_PAD src0_sel:WORD_1
	v_fma_f32 v32, -v29, v30, 1.0
	v_fmac_f32_e32 v30, v32, v30
	v_div_scale_f32 v32, vcc, v22, v24, v22
	v_mul_f32_e32 v35, v32, v30
	v_fma_f32 v40, -v29, v35, v32
	v_fmac_f32_e32 v35, v40, v30
	v_fma_f32 v29, -v29, v35, v32
	v_div_fmas_f32 v29, v29, v30, v35
	v_div_fixup_f32 v22, v29, v24, v22
	v_bfi_b32 v35, s2, v25, v23
	v_mul_f32_e32 v0, v22, v0
	v_pk_add_f32 v[22:23], v[34:35], v[210:211]
	v_bfi_b32 v35, s2, v27, v21
	v_mul_f32_e32 v20, v20, v23
	v_mul_f32_e32 v20, v22, v20
	v_mul_f32_e32 v22, 0xbfb8aa3b, v18
	v_exp_f32_e32 v22, v22
	v_mov_b32_e32 v210, v33
	v_add_f32_e32 v22, 1.0, v22
	v_div_scale_f32 v23, s[0:1], v22, v22, v18
	v_rcp_f32_e32 v24, v23
	s_nop 0
	v_fma_f32 v25, -v23, v24, 1.0
	v_fmac_f32_e32 v24, v25, v24
	v_div_scale_f32 v25, vcc, v18, v22, v18
	v_mul_f32_e32 v29, v25, v24
	v_fma_f32 v30, -v23, v29, v25
	v_fmac_f32_e32 v29, v30, v24
	v_fma_f32 v23, -v23, v29, v25
	v_div_fmas_f32 v23, v23, v24, v29
	v_div_fixup_f32 v18, v23, v22, v18
	v_mul_f32_e32 v18, v18, v20
	v_cvt_pk_f16_f32 v18, v0, v18
	v_mul_f32_e32 v0, 0.5, v26
	v_pk_add_f32 v[20:21], v[34:35], v[210:211]
	s_nop 0
	v_mul_f32_e32 v0, v0, v21
	v_mul_f32_e32 v0, v20, v0
	v_mul_f32_e32 v20, 0xbfb8aa3b, v19
	v_exp_f32_e32 v20, v20
	s_nop 0
	v_add_f32_e32 v20, 1.0, v20
	v_div_scale_f32 v21, s[0:1], v20, v20, v19
	v_rcp_f32_e32 v22, v21
	s_nop 0
	v_fma_f32 v23, -v21, v22, 1.0
	v_fmac_f32_e32 v22, v23, v22
	v_div_scale_f32 v23, vcc, v19, v20, v19
	v_mul_f32_e32 v24, v23, v22
	v_fma_f32 v25, -v21, v24, v23
	v_fmac_f32_e32 v24, v25, v22
	v_fma_f32 v21, -v21, v24, v23
	v_div_fmas_f32 v21, v21, v22, v24
	v_div_fixup_f32 v19, v21, v20, v19
	v_mul_f32_e32 v0, v19, v0
	v_cvt_pk_f16_f32 v19, v28, v0
	global_store_dwordx2 v[36:37], v[18:19], off offset:48
	s_nop 0
	s_waitcnt vmcnt(11)
	v_cvt_f32_f16_e32 v0, v182
	v_mul_f32_e32 v22, 0x3f3504f3, v0
	v_cmp_nlt_f32_e64 s[0:1], |v22|, 1.0
	s_and_saveexec_b64 s[2:3], s[0:1]
	s_xor_b64 s[0:1], exec, s[2:3]
	s_cbranch_execz .LBB0_850
; DI unsigned pk2(float a, float b) { f2_t v = {a, b}; bf2_t r = __builtin_convertvector(v, bf2_t); return __builtin_bit_cast(unsigned, r); }
; DI float bflo(unsigned u) { return (float)__builtin_bit_cast(bf2_t, u)[0]; }
; DI float bfhi(unsigned u) { return (float)__builtin_bit_cast(bf2_t, u)[1]; }
; DI float siluf_(float x) { return x / (1.f + __expf(-x)); }
; DI float geluf_(float x) { return 0.5f * x * (1.f + erff(x * 0.70710678118654752f)); }
; DI void sg_item(const Params& p, int l, int item, char* lds, int dry) {
;     ...
;     for (int a4 = 0; a4 < 4; ++a4) {
;       const int d = db * 32 + 8 * a4 + 4 * h;
;       const uint2 uv = *(const uint2*)(zr + UD + g * 64 + d);
;     ...
;       o.x = pk2(geluf_(bflo(uv.x)) * (acc[db][4 * a4] + bsv) * siluf_(bflo(gv.x)),
;                 geluf_(bfhi(uv.x)) * (acc[db][4 * a4 + 1] + bsv) * siluf_(bfhi(gv.x)));
;       o.y = pk2(geluf_(bflo(uv.y)) * (acc[db][4 * a4 + 2] + bsv) * siluf_(bflo(gv.y)),
;                 geluf_(bfhi(uv.y)) * (acc[db][4 * a4 + 3] + bsv) * siluf_(bfhi(gv.y)));
	v_fma_f32 v23, |v22|, s77, v224
	s_mov_b32 s2, 0x3b7cd369
	v_fma_f32 v23, |v22|, v23, s2
	s_mov_b32 s2, 0xbcc618b2
	v_fma_f32 v23, |v22|, v23, s2
	s_mov_b32 s2, 0x3dda74e4
	v_fma_f32 v23, |v22|, v23, s2
	s_mov_b32 s2, 0x3f228afd
	v_fma_f32 v23, |v22|, v23, s2
	s_mov_b32 s2, 0x3e03c728
	v_fma_f32 v23, |v22|, v23, s2
	v_fma_f32 v23, |v22|, v23, |v22|
	v_mul_f32_e32 v24, 0xbfb8aa3b, v23
	s_mov_b32 s2, 0xbfb8aa3b
	v_fma_f32 v25, v23, s2, -v24
	v_rndne_f32_e32 v26, v24
	v_fmac_f32_e32 v25, 0xb2a5705f, v23
	v_sub_f32_e32 v24, v24, v26
	v_add_f32_e32 v24, v24, v25
	v_cvt_i32_f32_e32 v25, v26
	v_exp_f32_e32 v24, v24
	s_mov_b32 s2, 0x42ce8ed0
	v_cmp_nlt_f32_e32 vcc, s2, v23
	s_mov_b32 s2, 0xc2b17218
	v_ldexp_f32 v24, v24, v25
	v_cndmask_b32_e32 v24, 0, v24, vcc
	v_cmp_ngt_f32_e32 vcc, s2, v23
	s_nop 1
	v_cndmask_b32_e32 v23, v225, v24, vcc
	v_sub_f32_e32 v24, 1.0, v23
.LBB0_850:
	s_andn2_saveexec_b64 s[0:1], s[0:1]
	v_mul_f32_e32 v23, v22, v22
	v_fmamk_f32 v24, v23, 0xba1345e1, v220
	v_fmaak_f32 v24, v23, v24, 0xbcdac9b8
	v_fmaak_f32 v24, v23, v24, 0x3de703be
	v_fmaak_f32 v24, v23, v24, 0xbec09330
	v_fmaak_f32 v23, v23, v24, 0x3e0375d0
	v_fma_f32 v24, |v22|, v23, |v22|
	s_or_b64 exec, exec, s[0:1]
	v_cvt_f32_f16_sdwa v20, v182 dst_sel:DWORD dst_unused:UNUSED_PAD src0_sel:WORD_1
	v_mul_f32_e32 v23, 0x3f3504f3, v20
	v_cmp_nlt_f32_e64 s[0:1], |v23|, 1.0
	s_and_saveexec_b64 s[2:3], s[0:1]
	s_xor_b64 s[0:1], exec, s[2:3]
	s_cbranch_execz .LBB0_854
	v_fma_f32 v25, |v23|, s77, v224
	s_mov_b32 s2, 0x3b7cd369
	v_fma_f32 v25, |v23|, v25, s2
	s_mov_b32 s2, 0xbcc618b2
	v_fma_f32 v25, |v23|, v25, s2
	s_mov_b32 s2, 0x3dda74e4
	v_fma_f32 v25, |v23|, v25, s2
	s_mov_b32 s2, 0x3f228afd
	v_fma_f32 v25, |v23|, v25, s2
	s_mov_b32 s2, 0x3e03c728
	v_fma_f32 v25, |v23|, v25, s2
	v_fma_f32 v25, |v23|, v25, |v23|
	v_mul_f32_e32 v26, 0xbfb8aa3b, v25
	s_mov_b32 s2, 0xbfb8aa3b
	v_fma_f32 v27, v25, s2, -v26
	v_rndne_f32_e32 v28, v26
	v_fmac_f32_e32 v27, 0xb2a5705f, v25
	v_sub_f32_e32 v26, v26, v28
	v_add_f32_e32 v26, v26, v27
	v_cvt_i32_f32_e32 v27, v28
	v_exp_f32_e32 v26, v26
	s_mov_b32 s2, 0x42ce8ed0
	v_cmp_nlt_f32_e32 vcc, s2, v25
	s_mov_b32 s2, 0xc2b17218
	v_ldexp_f32 v26, v26, v27
	v_cndmask_b32_e32 v26, 0, v26, vcc
	v_cmp_ngt_f32_e32 vcc, s2, v25
	s_nop 1
	v_cndmask_b32_e32 v25, v225, v26, vcc
	v_sub_f32_e32 v25, 1.0, v25
.LBB0_854:
	s_andn2_saveexec_b64 s[0:1], s[0:1]
	v_mul_f32_e32 v25, v23, v23
	v_fmamk_f32 v26, v25, 0xba1345e1, v220
	v_fmaak_f32 v26, v25, v26, 0xbcdac9b8
	v_fmaak_f32 v26, v25, v26, 0x3de703be
	v_fmaak_f32 v26, v25, v26, 0xbec09330
	v_fmaak_f32 v25, v25, v26, 0x3e0375d0
	v_fma_f32 v25, |v23|, v25, |v23|
	s_or_b64 exec, exec, s[0:1]
	v_cvt_f32_f16_e32 v29, v183
	v_mul_f32_e32 v28, 0x3f3504f3, v29
	v_cmp_nlt_f32_e64 s[0:1], |v28|, 1.0
	s_and_saveexec_b64 s[2:3], s[0:1]
	s_xor_b64 s[0:1], exec, s[2:3]
	s_cbranch_execz .LBB0_858
	v_fma_f32 v26, |v28|, s77, v224
	s_mov_b32 s2, 0x3b7cd369
	v_fma_f32 v26, |v28|, v26, s2
	s_mov_b32 s2, 0xbcc618b2
	v_fma_f32 v26, |v28|, v26, s2
	s_mov_b32 s2, 0x3dda74e4
	v_fma_f32 v26, |v28|, v26, s2
	s_mov_b32 s2, 0x3f228afd
	v_fma_f32 v26, |v28|, v26, s2
	s_mov_b32 s2, 0x3e03c728
	v_fma_f32 v26, |v28|, v26, s2
	v_fma_f32 v26, |v28|, v26, |v28|
	v_mul_f32_e32 v27, 0xbfb8aa3b, v26
	s_mov_b32 s2, 0xbfb8aa3b
	v_fma_f32 v30, v26, s2, -v27
	v_rndne_f32_e32 v31, v27
	v_fmac_f32_e32 v30, 0xb2a5705f, v26
	v_sub_f32_e32 v27, v27, v31
	v_add_f32_e32 v27, v27, v30
	v_cvt_i32_f32_e32 v30, v31
	v_exp_f32_e32 v27, v27
	s_mov_b32 s2, 0x42ce8ed0
	v_cmp_nlt_f32_e32 vcc, s2, v26
	s_mov_b32 s2, 0xc2b17218
	v_ldexp_f32 v27, v27, v30
	v_cndmask_b32_e32 v27, 0, v27, vcc
	v_cmp_ngt_f32_e32 vcc, s2, v26
	s_nop 1
	v_cndmask_b32_e32 v26, v225, v27, vcc
	v_sub_f32_e32 v30, 1.0, v26
.LBB0_858:
	s_andn2_saveexec_b64 s[0:1], s[0:1]
	v_mul_f32_e32 v26, v28, v28
	v_fmamk_f32 v27, v26, 0xba1345e1, v220
	v_fmaak_f32 v27, v26, v27, 0xbcdac9b8
	v_fmaak_f32 v27, v26, v27, 0x3de703be
	v_fmaak_f32 v27, v26, v27, 0xbec09330
	v_fmaak_f32 v26, v26, v27, 0x3e0375d0
	v_fma_f32 v30, |v28|, v26, |v28|
	s_or_b64 exec, exec, s[0:1]
	v_cvt_f32_f16_sdwa v26, v183 dst_sel:DWORD dst_unused:UNUSED_PAD src0_sel:WORD_1
	v_mul_f32_e32 v21, 0x3f3504f3, v26
	v_cmp_nlt_f32_e64 s[0:1], |v21|, 1.0
	s_and_saveexec_b64 s[2:3], s[0:1]
	s_xor_b64 s[0:1], exec, s[2:3]
	s_cbranch_execz .LBB0_862
	v_fma_f32 v27, |v21|, s77, v224
	s_mov_b32 s2, 0x3b7cd369
	v_fma_f32 v27, |v21|, v27, s2
	s_mov_b32 s2, 0xbcc618b2
	v_fma_f32 v27, |v21|, v27, s2
	s_mov_b32 s2, 0x3dda74e4
	v_fma_f32 v27, |v21|, v27, s2
	s_mov_b32 s2, 0x3f228afd
	v_fma_f32 v27, |v21|, v27, s2
	s_mov_b32 s2, 0x3e03c728
	v_fma_f32 v27, |v21|, v27, s2
	v_fma_f32 v27, |v21|, v27, |v21|
	v_mul_f32_e32 v31, 0xbfb8aa3b, v27
	s_mov_b32 s2, 0xbfb8aa3b
	v_fma_f32 v32, v27, s2, -v31
	v_rndne_f32_e32 v33, v31
	v_fmac_f32_e32 v32, 0xb2a5705f, v27
	v_sub_f32_e32 v31, v31, v33
	v_add_f32_e32 v31, v31, v32
	v_cvt_i32_f32_e32 v32, v33
	v_exp_f32_e32 v31, v31
	s_mov_b32 s2, 0x42ce8ed0
	v_cmp_nlt_f32_e32 vcc, s2, v27
	s_mov_b32 s2, 0xc2b17218
	v_ldexp_f32 v31, v31, v32
	v_cndmask_b32_e32 v31, 0, v31, vcc
	v_cmp_ngt_f32_e32 vcc, s2, v27
	s_nop 1
	v_cndmask_b32_e32 v27, v225, v31, vcc
	v_sub_f32_e32 v27, 1.0, v27
; DI unsigned pk2(float a, float b) { f2_t v = {a, b}; bf2_t r = __builtin_convertvector(v, bf2_t); return __builtin_bit_cast(unsigned, r); }
; DI float bflo(unsigned u) { return (float)__builtin_bit_cast(bf2_t, u)[0]; }
; DI float bfhi(unsigned u) { return (float)__builtin_bit_cast(bf2_t, u)[1]; }
; DI float siluf_(float x) { return x / (1.f + __expf(-x)); }
; DI float geluf_(float x) { return 0.5f * x * (1.f + erff(x * 0.70710678118654752f)); }
; DI void sg_item(const Params& p, int l, int item, char* lds, int dry) {
;     ...
;     for (int a4 = 0; a4 < 4; ++a4) {
;       const int d = db * 32 + 8 * a4 + 4 * h;
;       const uint2 uv = *(const uint2*)(zr + UD + g * 64 + d);
;       uint2* gp = (uint2*)(zr + GD + g * 64 + d);
;       const uint2 gv = *gp;
;       uint2 o;
;       o.x = pk2(geluf_(bflo(uv.x)) * (acc[db][4 * a4] + bsv) * siluf_(bflo(gv.x)),
;                 geluf_(bfhi(uv.x)) * (acc[db][4 * a4 + 1] + bsv) * siluf_(bfhi(gv.x)));
;       o.y = pk2(geluf_(bflo(uv.y)) * (acc[db][4 * a4 + 2] + bsv) * siluf_(bflo(gv.y)),
;                 geluf_(bfhi(uv.y)) * (acc[db][4 * a4 + 3] + bsv) * siluf_(bfhi(gv.y)));
;       if (dry) gp = (uint2*)(p.blkscr + (size_t)blockIdx.x * 8 * 256 + tid + ((db * 4 + a4) >> 1) * 256) + (a4 & 1);
;       *gp = o;
.LBB0_862:
	s_andn2_saveexec_b64 s[0:1], s[0:1]
	v_mul_f32_e32 v27, v21, v21
	v_fmamk_f32 v31, v27, 0xba1345e1, v220
	v_fmaak_f32 v31, v27, v31, 0xbcdac9b8
	v_fmaak_f32 v31, v27, v31, 0x3de703be
	v_fmaak_f32 v31, v27, v31, 0xbec09330
	v_fmaak_f32 v27, v27, v31, 0x3e0375d0
	v_fma_f32 v27, |v21|, v27, |v21|
	s_or_b64 exec, exec, s[0:1]
	s_brev_b32 s2, -2
	v_bfi_b32 v28, s2, v30, v28
	v_mul_f32_e32 v29, 0.5, v29
	v_add_f32_e32 v28, 1.0, v28
	v_mul_f32_e32 v28, v29, v28
	v_add_f32_e32 v4, v4, v34
	v_mul_f32_e32 v4, v4, v28
	s_waitcnt vmcnt(10)
	v_cvt_f32_f16_e32 v28, v185
	v_mul_f32_e32 v0, 0.5, v0
	v_add_f32_e32 v2, v2, v34
	v_mov_b32_e32 v210, v3
	v_mul_f32_e32 v29, 0xbfb8aa3b, v28
	v_exp_f32_e32 v29, v29
	s_nop 0
	v_add_f32_e32 v29, 1.0, v29
	v_div_scale_f32 v30, s[0:1], v29, v29, v28
	v_rcp_f32_e32 v31, v30
	s_nop 0
	v_fma_f32 v32, -v30, v31, 1.0
	v_fmac_f32_e32 v31, v32, v31
	v_div_scale_f32 v32, vcc, v28, v29, v28
	v_mul_f32_e32 v33, v32, v31
	v_fma_f32 v35, -v30, v33, v32
	v_fmac_f32_e32 v33, v35, v31
	v_fma_f32 v30, -v30, v33, v32
	v_div_fmas_f32 v30, v30, v31, v33
	v_div_fixup_f32 v28, v30, v29, v28
	v_mul_f32_e32 v28, v28, v4
	v_bfi_b32 v4, s2, v24, v22
	v_add_f32_e32 v4, 1.0, v4
	v_mul_f32_e32 v0, v0, v4
	v_mul_f32_e32 v0, v2, v0
	v_cvt_f32_f16_e32 v2, v184
	v_bfi_b32 v35, s2, v25, v23
	v_mul_f32_e32 v4, 0xbfb8aa3b, v2
	v_exp_f32_e32 v4, v4
	s_nop 0
	v_add_f32_e32 v4, 1.0, v4
	v_div_scale_f32 v22, s[0:1], v4, v4, v2
	v_rcp_f32_e32 v24, v22
	s_nop 0
	v_fma_f32 v29, -v22, v24, 1.0
	v_fmac_f32_e32 v24, v29, v24
	v_div_scale_f32 v29, vcc, v2, v4, v2
	v_mul_f32_e32 v30, v29, v24
	v_fma_f32 v31, -v22, v30, v29
	v_fmac_f32_e32 v30, v31, v24
	v_fma_f32 v22, -v22, v30, v29
	v_div_fmas_f32 v22, v22, v24, v30
	v_div_fixup_f32 v2, v22, v4, v2
	v_mul_f32_e32 v0, v2, v0
	v_mul_f32_e32 v4, 0.5, v20
	v_pk_add_f32 v[2:3], v[210:211], v[34:35]
	v_bfi_b32 v35, s2, v27, v21
	v_mul_f32_e32 v3, v4, v3
	v_mul_f32_e32 v2, v2, v3
	v_cvt_f32_f16_sdwa v3, v184 dst_sel:DWORD dst_unused:UNUSED_PAD src0_sel:WORD_1
	v_mov_b32_e32 v210, v5
	v_mul_f32_e32 v4, 0xbfb8aa3b, v3
	v_exp_f32_e32 v4, v4
	s_nop 0
	v_add_f32_e32 v4, 1.0, v4
	v_div_scale_f32 v18, s[0:1], v4, v4, v3
	v_rcp_f32_e32 v20, v18
	s_nop 0
	v_fma_f32 v22, -v18, v20, 1.0
	v_fmac_f32_e32 v20, v22, v20
	v_div_scale_f32 v22, vcc, v3, v4, v3
	v_mul_f32_e32 v23, v22, v20
	v_fma_f32 v24, -v18, v23, v22
	v_fmac_f32_e32 v23, v24, v20
	v_fma_f32 v18, -v18, v23, v22
	v_div_fmas_f32 v18, v18, v20, v23
	v_div_fixup_f32 v3, v18, v4, v3
	v_mul_f32_e32 v2, v3, v2
	v_cvt_f32_f16_sdwa v3, v185 dst_sel:DWORD dst_unused:UNUSED_PAD src0_sel:WORD_1
	v_cvt_pk_f16_f32 v2, v0, v2
	v_mul_f32_e32 v0, 0.5, v26
	v_pk_add_f32 v[4:5], v[210:211], v[34:35]
	s_nop 0
	v_mul_f32_e32 v0, v0, v5
	v_mul_f32_e32 v0, v4, v0
	v_mul_f32_e32 v4, 0xbfb8aa3b, v3
	v_exp_f32_e32 v4, v4
	s_nop 0
	v_add_f32_e32 v4, 1.0, v4
	v_div_scale_f32 v5, s[0:1], v4, v4, v3
	v_rcp_f32_e32 v18, v5
	s_nop 0
	v_fma_f32 v19, -v5, v18, 1.0
	v_fmac_f32_e32 v18, v19, v18
	v_div_scale_f32 v19, vcc, v3, v4, v3
	v_mul_f32_e32 v20, v19, v18
	v_fma_f32 v21, -v5, v20, v19
	v_fmac_f32_e32 v20, v21, v18
	v_fma_f32 v5, -v5, v20, v19
	v_div_fmas_f32 v5, v5, v18, v20
	v_div_fixup_f32 v3, v5, v4, v3
	v_mul_f32_e32 v0, v3, v0
	v_cvt_pk_f16_f32 v3, v28, v0
	global_store_dwordx2 v[36:37], v[2:3], off offset:64
	s_nop 0
	s_waitcnt vmcnt(10)
	v_cvt_f32_f16_e32 v0, v186
	v_mul_f32_e32 v18, 0x3f3504f3, v0
	v_cmp_nlt_f32_e64 s[0:1], |v18|, 1.0
	s_and_saveexec_b64 s[2:3], s[0:1]
	s_xor_b64 s[0:1], exec, s[2:3]
	s_cbranch_execz .LBB0_866
	v_fma_f32 v19, |v18|, s77, v224
	s_mov_b32 s2, 0x3b7cd369
	v_fma_f32 v19, |v18|, v19, s2
	s_mov_b32 s2, 0xbcc618b2
	v_fma_f32 v19, |v18|, v19, s2
	s_mov_b32 s2, 0x3dda74e4
	v_fma_f32 v19, |v18|, v19, s2
	s_mov_b32 s2, 0x3f228afd
	v_fma_f32 v19, |v18|, v19, s2
	s_mov_b32 s2, 0x3e03c728
	v_fma_f32 v19, |v18|, v19, s2
	v_fma_f32 v19, |v18|, v19, |v18|
	v_mul_f32_e32 v20, 0xbfb8aa3b, v19
	s_mov_b32 s2, 0xbfb8aa3b
	v_fma_f32 v21, v19, s2, -v20
	v_rndne_f32_e32 v22, v20
	v_fmac_f32_e32 v21, 0xb2a5705f, v19
	v_sub_f32_e32 v20, v20, v22
	v_add_f32_e32 v20, v20, v21
	v_cvt_i32_f32_e32 v21, v22
	v_exp_f32_e32 v20, v20
	s_mov_b32 s2, 0x42ce8ed0
	v_cmp_nlt_f32_e32 vcc, s2, v19
	s_mov_b32 s2, 0xc2b17218
	v_ldexp_f32 v20, v20, v21
	v_cndmask_b32_e32 v20, 0, v20, vcc
	v_cmp_ngt_f32_e32 vcc, s2, v19
	s_nop 1
	v_cndmask_b32_e32 v19, v225, v20, vcc
	v_sub_f32_e32 v20, 1.0, v19
.LBB0_866:
	s_andn2_saveexec_b64 s[0:1], s[0:1]
	v_mul_f32_e32 v19, v18, v18
	v_fmamk_f32 v20, v19, 0xba1345e1, v220
	v_fmaak_f32 v20, v19, v20, 0xbcdac9b8
	v_fmaak_f32 v20, v19, v20, 0x3de703be
	v_fmaak_f32 v20, v19, v20, 0xbec09330
	v_fmaak_f32 v19, v19, v20, 0x3e0375d0
	v_fma_f32 v20, |v18|, v19, |v18|
	s_or_b64 exec, exec, s[0:1]
	v_cvt_f32_f16_sdwa v4, v186 dst_sel:DWORD dst_unused:UNUSED_PAD src0_sel:WORD_1
	v_mul_f32_e32 v19, 0x3f3504f3, v4
	v_cmp_nlt_f32_e64 s[0:1], |v19|, 1.0
	s_and_saveexec_b64 s[2:3], s[0:1]
	s_xor_b64 s[0:1], exec, s[2:3]
	s_cbranch_execz .LBB0_870
	v_fma_f32 v21, |v19|, s77, v224
	s_mov_b32 s2, 0x3b7cd369
	v_fma_f32 v21, |v19|, v21, s2
	s_mov_b32 s2, 0xbcc618b2
	v_fma_f32 v21, |v19|, v21, s2
	s_mov_b32 s2, 0x3dda74e4
	v_fma_f32 v21, |v19|, v21, s2
	s_mov_b32 s2, 0x3f228afd
	v_fma_f32 v21, |v19|, v21, s2
	s_mov_b32 s2, 0x3e03c728
	v_fma_f32 v21, |v19|, v21, s2
	v_fma_f32 v21, |v19|, v21, |v19|
	v_mul_f32_e32 v22, 0xbfb8aa3b, v21
	s_mov_b32 s2, 0xbfb8aa3b
	v_fma_f32 v23, v21, s2, -v22
	v_rndne_f32_e32 v24, v22
	v_fmac_f32_e32 v23, 0xb2a5705f, v21
	v_sub_f32_e32 v22, v22, v24
	v_add_f32_e32 v22, v22, v23
	v_cvt_i32_f32_e32 v23, v24
	v_exp_f32_e32 v22, v22
	s_mov_b32 s2, 0x42ce8ed0
	v_cmp_nlt_f32_e32 vcc, s2, v21
	s_mov_b32 s2, 0xc2b17218
	v_ldexp_f32 v22, v22, v23
	v_cndmask_b32_e32 v22, 0, v22, vcc
	v_cmp_ngt_f32_e32 vcc, s2, v21
	s_nop 1
	v_cndmask_b32_e32 v21, v225, v22, vcc
	v_sub_f32_e32 v21, 1.0, v21
; DI unsigned pk2(float a, float b) { f2_t v = {a, b}; bf2_t r = __builtin_convertvector(v, bf2_t); return __builtin_bit_cast(unsigned, r); }
; DI float bflo(unsigned u) { return (float)__builtin_bit_cast(bf2_t, u)[0]; }
; DI float bfhi(unsigned u) { return (float)__builtin_bit_cast(bf2_t, u)[1]; }
; DI float siluf_(float x) { return x / (1.f + __expf(-x)); }
; DI float geluf_(float x) { return 0.5f * x * (1.f + erff(x * 0.70710678118654752f)); }
; DI void sg_item(const Params& p, int l, int item, char* lds, int dry) {
;     ...
;     for (int a4 = 0; a4 < 4; ++a4) {
;       const int d = db * 32 + 8 * a4 + 4 * h;
;       const uint2 uv = *(const uint2*)(zr + UD + g * 64 + d);
;       uint2* gp = (uint2*)(zr + GD + g * 64 + d);
;       const uint2 gv = *gp;
;       uint2 o;
;       o.x = pk2(geluf_(bflo(uv.x)) * (acc[db][4 * a4] + bsv) * siluf_(bflo(gv.x)),
;                 geluf_(bfhi(uv.x)) * (acc[db][4 * a4 + 1] + bsv) * siluf_(bfhi(gv.x)));
;       o.y = pk2(geluf_(bflo(uv.y)) * (acc[db][4 * a4 + 2] + bsv) * siluf_(bflo(gv.y)),
;                 geluf_(bfhi(uv.y)) * (acc[db][4 * a4 + 3] + bsv) * siluf_(bfhi(gv.y)));
;       if (dry) gp = (uint2*)(p.blkscr + (size_t)blockIdx.x * 8 * 256 + tid + ((db * 4 + a4) >> 1) * 256) + (a4 & 1);
;       *gp = o;
.LBB0_870:
	s_andn2_saveexec_b64 s[0:1], s[0:1]
	v_mul_f32_e32 v21, v19, v19
	v_fmamk_f32 v22, v21, 0xba1345e1, v220
	v_fmaak_f32 v22, v21, v22, 0xbcdac9b8
	v_fmaak_f32 v22, v21, v22, 0x3de703be
	v_fmaak_f32 v22, v21, v22, 0xbec09330
	v_fmaak_f32 v21, v21, v22, 0x3e0375d0
	v_fma_f32 v21, |v19|, v21, |v19|
	s_or_b64 exec, exec, s[0:1]
	v_cvt_f32_f16_e32 v25, v187
	v_mul_f32_e32 v24, 0x3f3504f3, v25
	v_cmp_nlt_f32_e64 s[0:1], |v24|, 1.0
	s_and_saveexec_b64 s[2:3], s[0:1]
	s_xor_b64 s[0:1], exec, s[2:3]
	s_cbranch_execz .LBB0_874
	v_fma_f32 v22, |v24|, s77, v224
	s_mov_b32 s2, 0x3b7cd369
	v_fma_f32 v22, |v24|, v22, s2
	s_mov_b32 s2, 0xbcc618b2
	v_fma_f32 v22, |v24|, v22, s2
	s_mov_b32 s2, 0x3dda74e4
	v_fma_f32 v22, |v24|, v22, s2
	s_mov_b32 s2, 0x3f228afd
	v_fma_f32 v22, |v24|, v22, s2
	s_mov_b32 s2, 0x3e03c728
	v_fma_f32 v22, |v24|, v22, s2
	v_fma_f32 v22, |v24|, v22, |v24|
	v_mul_f32_e32 v23, 0xbfb8aa3b, v22
	s_mov_b32 s2, 0xbfb8aa3b
	v_fma_f32 v26, v22, s2, -v23
	v_rndne_f32_e32 v27, v23
	v_fmac_f32_e32 v26, 0xb2a5705f, v22
	v_sub_f32_e32 v23, v23, v27
	v_add_f32_e32 v23, v23, v26
	v_cvt_i32_f32_e32 v26, v27
	v_exp_f32_e32 v23, v23
	s_mov_b32 s2, 0x42ce8ed0
	v_cmp_nlt_f32_e32 vcc, s2, v22
	s_mov_b32 s2, 0xc2b17218
	v_ldexp_f32 v23, v23, v26
	v_cndmask_b32_e32 v23, 0, v23, vcc
	v_cmp_ngt_f32_e32 vcc, s2, v22
	s_nop 1
	v_cndmask_b32_e32 v22, v225, v23, vcc
	v_sub_f32_e32 v26, 1.0, v22
.LBB0_874:
	s_andn2_saveexec_b64 s[0:1], s[0:1]
	v_mul_f32_e32 v22, v24, v24
	v_fmamk_f32 v23, v22, 0xba1345e1, v220
	v_fmaak_f32 v23, v22, v23, 0xbcdac9b8
	v_fmaak_f32 v23, v22, v23, 0x3de703be
	v_fmaak_f32 v23, v22, v23, 0xbec09330
	v_fmaak_f32 v22, v22, v23, 0x3e0375d0
	v_fma_f32 v26, |v24|, v22, |v24|
	s_or_b64 exec, exec, s[0:1]
	v_cvt_f32_f16_sdwa v22, v187 dst_sel:DWORD dst_unused:UNUSED_PAD src0_sel:WORD_1
	v_mul_f32_e32 v5, 0x3f3504f3, v22
	v_cmp_nlt_f32_e64 s[0:1], |v5|, 1.0
	s_and_saveexec_b64 s[2:3], s[0:1]
	s_xor_b64 s[0:1], exec, s[2:3]
	s_cbranch_execz .LBB0_878
	v_fma_f32 v23, |v5|, s77, v224
	s_mov_b32 s2, 0x3b7cd369
	v_fma_f32 v23, |v5|, v23, s2
	s_mov_b32 s2, 0xbcc618b2
	v_fma_f32 v23, |v5|, v23, s2
	s_mov_b32 s2, 0x3dda74e4
	v_fma_f32 v23, |v5|, v23, s2
	s_mov_b32 s2, 0x3f228afd
	v_fma_f32 v23, |v5|, v23, s2
	s_mov_b32 s2, 0x3e03c728
	v_fma_f32 v23, |v5|, v23, s2
	v_fma_f32 v23, |v5|, v23, |v5|
	v_mul_f32_e32 v27, 0xbfb8aa3b, v23
	s_mov_b32 s2, 0xbfb8aa3b
	v_fma_f32 v28, v23, s2, -v27
	v_rndne_f32_e32 v29, v27
	v_fmac_f32_e32 v28, 0xb2a5705f, v23
	v_sub_f32_e32 v27, v27, v29
	v_add_f32_e32 v27, v27, v28
	v_cvt_i32_f32_e32 v28, v29
	v_exp_f32_e32 v27, v27
	s_mov_b32 s2, 0x42ce8ed0
	v_cmp_nlt_f32_e32 vcc, s2, v23
	s_mov_b32 s2, 0xc2b17218
	v_ldexp_f32 v27, v27, v28
	v_cndmask_b32_e32 v27, 0, v27, vcc
	v_cmp_ngt_f32_e32 vcc, s2, v23
	s_nop 1
	v_cndmask_b32_e32 v23, v225, v27, vcc
	v_sub_f32_e32 v23, 1.0, v23
.LBB0_878:
	s_andn2_saveexec_b64 s[0:1], s[0:1]
	v_mul_f32_e32 v23, v5, v5
	v_fmamk_f32 v27, v23, 0xba1345e1, v220
	v_fmaak_f32 v27, v23, v27, 0xbcdac9b8
	v_fmaak_f32 v27, v23, v27, 0x3de703be
	v_fmaak_f32 v27, v23, v27, 0xbec09330
	v_fmaak_f32 v23, v23, v27, 0x3e0375d0
	v_fma_f32 v23, |v5|, v23, |v5|
	s_or_b64 exec, exec, s[0:1]
	s_brev_b32 s2, -2
	v_bfi_b32 v24, s2, v26, v24
	v_mul_f32_e32 v25, 0.5, v25
	v_add_f32_e32 v24, 1.0, v24
	v_mul_f32_e32 v24, v25, v24
	v_add_f32_e32 v8, v8, v34
	v_mul_f32_e32 v8, v8, v24
	s_waitcnt vmcnt(9)
	v_cvt_f32_f16_e32 v24, v189
	v_bfi_b32 v18, s2, v20, v18
	v_mul_f32_e32 v0, 0.5, v0
	v_add_f32_e32 v18, 1.0, v18
	v_mul_f32_e32 v25, 0xbfb8aa3b, v24
	v_exp_f32_e32 v25, v25
	v_mul_f32_e32 v0, v0, v18
	v_add_f32_e32 v6, v6, v34
	v_mul_f32_e32 v0, v6, v0
	v_add_f32_e32 v25, 1.0, v25
	v_div_scale_f32 v26, s[0:1], v25, v25, v24
	v_rcp_f32_e32 v27, v26
	v_cvt_f32_f16_e32 v6, v188
	v_cvt_f32_f16_sdwa v2, v188 dst_sel:DWORD dst_unused:UNUSED_PAD src0_sel:WORD_1
	v_bfi_b32 v35, s2, v21, v19
	v_fma_f32 v28, -v26, v27, 1.0
	v_fmac_f32_e32 v27, v28, v27
	v_div_scale_f32 v28, vcc, v24, v25, v24
	v_mul_f32_e32 v18, 0xbfb8aa3b, v6
	v_mul_f32_e32 v29, v28, v27
	v_exp_f32_e32 v18, v18
	v_fma_f32 v30, -v26, v29, v28
	v_fmac_f32_e32 v29, v30, v27
	v_fma_f32 v26, -v26, v29, v28
	v_div_fmas_f32 v26, v26, v27, v29
	v_add_f32_e32 v18, 1.0, v18
	v_div_fixup_f32 v24, v26, v25, v24
	v_div_scale_f32 v20, s[0:1], v18, v18, v6
	v_mul_f32_e32 v8, v24, v8
	v_rcp_f32_e32 v24, v20
	v_mov_b32_e32 v210, v7
	v_mul_f32_e32 v4, 0.5, v4
	v_cvt_f32_f16_sdwa v3, v189 dst_sel:DWORD dst_unused:UNUSED_PAD src0_sel:WORD_1
	v_fma_f32 v25, -v20, v24, 1.0
	v_fmac_f32_e32 v24, v25, v24
	v_div_scale_f32 v25, vcc, v6, v18, v6
	v_mul_f32_e32 v26, v25, v24
	v_fma_f32 v27, -v20, v26, v25
	v_fmac_f32_e32 v26, v27, v24
	v_fma_f32 v20, -v20, v26, v25
	v_div_fmas_f32 v20, v20, v24, v26
	v_div_fixup_f32 v6, v20, v18, v6
	v_mul_f32_e32 v0, v6, v0
	v_pk_add_f32 v[6:7], v[210:211], v[34:35]
	v_bfi_b32 v35, s2, v23, v5
	v_mul_f32_e32 v4, v4, v7
	v_mul_f32_e32 v4, v6, v4
	v_mul_f32_e32 v6, 0xbfb8aa3b, v2
	v_exp_f32_e32 v6, v6
	v_mov_b32_e32 v210, v9
	v_add_f32_e32 v6, 1.0, v6
	v_div_scale_f32 v7, s[0:1], v6, v6, v2
	v_rcp_f32_e32 v18, v7
	s_nop 0
	v_fma_f32 v19, -v7, v18, 1.0
	v_fmac_f32_e32 v18, v19, v18
	v_div_scale_f32 v19, vcc, v2, v6, v2
	v_mul_f32_e32 v20, v19, v18
	v_fma_f32 v21, -v7, v20, v19
	v_fmac_f32_e32 v20, v21, v18
	v_fma_f32 v7, -v7, v20, v19
	v_div_fmas_f32 v7, v7, v18, v20
	v_div_fixup_f32 v2, v7, v6, v2
	v_mul_f32_e32 v2, v2, v4
	v_cvt_pk_f16_f32 v2, v0, v2
	v_mul_f32_e32 v0, 0.5, v22
	v_pk_add_f32 v[4:5], v[210:211], v[34:35]
	s_nop 0
	v_mul_f32_e32 v0, v0, v5
	v_mul_f32_e32 v0, v4, v0
	v_mul_f32_e32 v4, 0xbfb8aa3b, v3
	v_exp_f32_e32 v4, v4
	s_nop 0
	v_add_f32_e32 v4, 1.0, v4
	v_div_scale_f32 v5, s[0:1], v4, v4, v3
	v_rcp_f32_e32 v6, v5
	s_nop 0
	v_fma_f32 v7, -v5, v6, 1.0
	v_fmac_f32_e32 v6, v7, v6
	v_div_scale_f32 v7, vcc, v3, v4, v3
	v_mul_f32_e32 v9, v7, v6
	v_fma_f32 v18, -v5, v9, v7
	v_fmac_f32_e32 v9, v18, v6
	v_fma_f32 v5, -v5, v9, v7
	v_div_fmas_f32 v5, v5, v6, v9
	v_div_fixup_f32 v3, v5, v4, v3
	v_mul_f32_e32 v0, v3, v0
	v_cvt_pk_f16_f32 v3, v8, v0
	global_store_dwordx2 v[36:37], v[2:3], off offset:80
	s_nop 0
	s_waitcnt vmcnt(9)
	v_cvt_f32_f16_e32 v0, v190
	v_mul_f32_e32 v6, 0x3f3504f3, v0
	v_cmp_nlt_f32_e64 s[0:1], |v6|, 1.0
	s_and_saveexec_b64 s[2:3], s[0:1]
	s_xor_b64 s[0:1], exec, s[2:3]
	s_cbranch_execz .LBB0_882
; DI unsigned pk2(float a, float b) { f2_t v = {a, b}; bf2_t r = __builtin_convertvector(v, bf2_t); return __builtin_bit_cast(unsigned, r); }
; DI float bflo(unsigned u) { return (float)__builtin_bit_cast(bf2_t, u)[0]; }
; DI float bfhi(unsigned u) { return (float)__builtin_bit_cast(bf2_t, u)[1]; }
; DI float siluf_(float x) { return x / (1.f + __expf(-x)); }
; DI float geluf_(float x) { return 0.5f * x * (1.f + erff(x * 0.70710678118654752f)); }
; DI void sg_item(const Params& p, int l, int item, char* lds, int dry) {
;     ...
;     for (int a4 = 0; a4 < 4; ++a4) {
;       const int d = db * 32 + 8 * a4 + 4 * h;
;       const uint2 uv = *(const uint2*)(zr + UD + g * 64 + d);
;     ...
;       o.x = pk2(geluf_(bflo(uv.x)) * (acc[db][4 * a4] + bsv) * siluf_(bflo(gv.x)),
;                 geluf_(bfhi(uv.x)) * (acc[db][4 * a4 + 1] + bsv) * siluf_(bfhi(gv.x)));
;       o.y = pk2(geluf_(bflo(uv.y)) * (acc[db][4 * a4 + 2] + bsv) * siluf_(bflo(gv.y)),
;                 geluf_(bfhi(uv.y)) * (acc[db][4 * a4 + 3] + bsv) * siluf_(bfhi(gv.y)));
	v_fma_f32 v7, |v6|, s77, v224
	s_mov_b32 s2, 0x3b7cd369
	v_fma_f32 v7, |v6|, v7, s2
	s_mov_b32 s2, 0xbcc618b2
	v_fma_f32 v7, |v6|, v7, s2
	s_mov_b32 s2, 0x3dda74e4
	v_fma_f32 v7, |v6|, v7, s2
	s_mov_b32 s2, 0x3f228afd
	v_fma_f32 v7, |v6|, v7, s2
	s_mov_b32 s2, 0x3e03c728
	v_fma_f32 v7, |v6|, v7, s2
	v_fma_f32 v7, |v6|, v7, |v6|
	v_mul_f32_e32 v8, 0xbfb8aa3b, v7
	s_mov_b32 s2, 0xbfb8aa3b
	v_fma_f32 v9, v7, s2, -v8
	v_rndne_f32_e32 v18, v8
	v_fmac_f32_e32 v9, 0xb2a5705f, v7
	v_sub_f32_e32 v8, v8, v18
	v_add_f32_e32 v8, v8, v9
	v_cvt_i32_f32_e32 v9, v18
	v_exp_f32_e32 v8, v8
	s_mov_b32 s2, 0x42ce8ed0
	v_cmp_nlt_f32_e32 vcc, s2, v7
	s_mov_b32 s2, 0xc2b17218
	v_ldexp_f32 v8, v8, v9
	v_cndmask_b32_e32 v8, 0, v8, vcc
	v_cmp_ngt_f32_e32 vcc, s2, v7
	s_nop 1
	v_cndmask_b32_e32 v7, v225, v8, vcc
	v_sub_f32_e32 v8, 1.0, v7
.LBB0_882:
	s_andn2_saveexec_b64 s[0:1], s[0:1]
	v_mul_f32_e32 v7, v6, v6
	v_fmamk_f32 v8, v7, 0xba1345e1, v220
	v_fmaak_f32 v8, v7, v8, 0xbcdac9b8
	v_fmaak_f32 v8, v7, v8, 0x3de703be
	v_fmaak_f32 v8, v7, v8, 0xbec09330
	v_fmaak_f32 v7, v7, v8, 0x3e0375d0
	v_fma_f32 v8, |v6|, v7, |v6|
	s_or_b64 exec, exec, s[0:1]
	v_cvt_f32_f16_sdwa v4, v190 dst_sel:DWORD dst_unused:UNUSED_PAD src0_sel:WORD_1
	v_mul_f32_e32 v7, 0x3f3504f3, v4
	v_cmp_nlt_f32_e64 s[0:1], |v7|, 1.0
	s_and_saveexec_b64 s[2:3], s[0:1]
	s_xor_b64 s[0:1], exec, s[2:3]
	s_cbranch_execz .LBB0_886
	v_fma_f32 v9, |v7|, s77, v224
	s_mov_b32 s2, 0x3b7cd369
	v_fma_f32 v9, |v7|, v9, s2
	s_mov_b32 s2, 0xbcc618b2
	v_fma_f32 v9, |v7|, v9, s2
	s_mov_b32 s2, 0x3dda74e4
	v_fma_f32 v9, |v7|, v9, s2
	s_mov_b32 s2, 0x3f228afd
	v_fma_f32 v9, |v7|, v9, s2
	s_mov_b32 s2, 0x3e03c728
	v_fma_f32 v9, |v7|, v9, s2
	v_fma_f32 v9, |v7|, v9, |v7|
	v_mul_f32_e32 v18, 0xbfb8aa3b, v9
	s_mov_b32 s2, 0xbfb8aa3b
	v_fma_f32 v19, v9, s2, -v18
	v_rndne_f32_e32 v20, v18
	v_fmac_f32_e32 v19, 0xb2a5705f, v9
	v_sub_f32_e32 v18, v18, v20
	v_add_f32_e32 v18, v18, v19
	v_cvt_i32_f32_e32 v19, v20
	v_exp_f32_e32 v18, v18
	s_mov_b32 s2, 0x42ce8ed0
	v_cmp_nlt_f32_e32 vcc, s2, v9
	s_mov_b32 s2, 0xc2b17218
	v_ldexp_f32 v18, v18, v19
	v_cndmask_b32_e32 v18, 0, v18, vcc
	v_cmp_ngt_f32_e32 vcc, s2, v9
	s_nop 1
	v_cndmask_b32_e32 v9, v225, v18, vcc
	v_sub_f32_e32 v9, 1.0, v9
.LBB0_886:
	s_andn2_saveexec_b64 s[0:1], s[0:1]
	v_mul_f32_e32 v9, v7, v7
	v_fmamk_f32 v18, v9, 0xba1345e1, v220
	v_fmaak_f32 v18, v9, v18, 0xbcdac9b8
	v_fmaak_f32 v18, v9, v18, 0x3de703be
	v_fmaak_f32 v18, v9, v18, 0xbec09330
	v_fmaak_f32 v9, v9, v18, 0x3e0375d0
	v_fma_f32 v9, |v7|, v9, |v7|
	s_or_b64 exec, exec, s[0:1]
	v_cvt_f32_f16_e32 v21, v191
	v_mul_f32_e32 v20, 0x3f3504f3, v21
	v_cmp_nlt_f32_e64 s[0:1], |v20|, 1.0
	s_and_saveexec_b64 s[2:3], s[0:1]
	s_xor_b64 s[0:1], exec, s[2:3]
	s_cbranch_execz .LBB0_890
	v_fma_f32 v18, |v20|, s77, v224
	s_mov_b32 s2, 0x3b7cd369
	v_fma_f32 v18, |v20|, v18, s2
	s_mov_b32 s2, 0xbcc618b2
	v_fma_f32 v18, |v20|, v18, s2
	s_mov_b32 s2, 0x3dda74e4
	v_fma_f32 v18, |v20|, v18, s2
	s_mov_b32 s2, 0x3f228afd
	v_fma_f32 v18, |v20|, v18, s2
	s_mov_b32 s2, 0x3e03c728
	v_fma_f32 v18, |v20|, v18, s2
	v_fma_f32 v18, |v20|, v18, |v20|
	v_mul_f32_e32 v19, 0xbfb8aa3b, v18
	s_mov_b32 s2, 0xbfb8aa3b
	v_fma_f32 v22, v18, s2, -v19
	v_rndne_f32_e32 v23, v19
	v_fmac_f32_e32 v22, 0xb2a5705f, v18
	v_sub_f32_e32 v19, v19, v23
	v_add_f32_e32 v19, v19, v22
	v_cvt_i32_f32_e32 v22, v23
	v_exp_f32_e32 v19, v19
	s_mov_b32 s2, 0x42ce8ed0
	v_cmp_nlt_f32_e32 vcc, s2, v18
	s_mov_b32 s2, 0xc2b17218
	v_ldexp_f32 v19, v19, v22
	v_cndmask_b32_e32 v19, 0, v19, vcc
	v_cmp_ngt_f32_e32 vcc, s2, v18
	s_nop 1
	v_cndmask_b32_e32 v18, v225, v19, vcc
	v_sub_f32_e32 v22, 1.0, v18
.LBB0_890:
	s_andn2_saveexec_b64 s[0:1], s[0:1]
	v_mul_f32_e32 v18, v20, v20
	v_fmamk_f32 v19, v18, 0xba1345e1, v220
	v_fmaak_f32 v19, v18, v19, 0xbcdac9b8
	v_fmaak_f32 v19, v18, v19, 0x3de703be
	v_fmaak_f32 v19, v18, v19, 0xbec09330
	v_fmaak_f32 v18, v18, v19, 0x3e0375d0
	v_fma_f32 v22, |v20|, v18, |v20|
	s_or_b64 exec, exec, s[0:1]
	v_cvt_f32_f16_sdwa v18, v191 dst_sel:DWORD dst_unused:UNUSED_PAD src0_sel:WORD_1
	v_mul_f32_e32 v5, 0x3f3504f3, v18
	v_cmp_nlt_f32_e64 s[0:1], |v5|, 1.0
	s_and_saveexec_b64 s[2:3], s[0:1]
	s_xor_b64 s[0:1], exec, s[2:3]
	s_cbranch_execz .LBB0_894
	v_fma_f32 v19, |v5|, s77, v224
	s_mov_b32 s2, 0x3b7cd369
	v_fma_f32 v19, |v5|, v19, s2
	s_mov_b32 s2, 0xbcc618b2
	v_fma_f32 v19, |v5|, v19, s2
	s_mov_b32 s2, 0x3dda74e4
	v_fma_f32 v19, |v5|, v19, s2
	s_mov_b32 s2, 0x3f228afd
	v_fma_f32 v19, |v5|, v19, s2
	s_mov_b32 s2, 0x3e03c728
	v_fma_f32 v19, |v5|, v19, s2
	v_fma_f32 v19, |v5|, v19, |v5|
	v_mul_f32_e32 v23, 0xbfb8aa3b, v19
	s_mov_b32 s2, 0xbfb8aa3b
	v_fma_f32 v24, v19, s2, -v23
	v_rndne_f32_e32 v25, v23
	v_fmac_f32_e32 v24, 0xb2a5705f, v19
	v_sub_f32_e32 v23, v23, v25
	v_add_f32_e32 v23, v23, v24
	v_cvt_i32_f32_e32 v24, v25
	v_exp_f32_e32 v23, v23
	s_mov_b32 s2, 0x42ce8ed0
	v_cmp_nlt_f32_e32 vcc, s2, v19
	s_mov_b32 s2, 0xc2b17218
	v_ldexp_f32 v23, v23, v24
	v_cndmask_b32_e32 v23, 0, v23, vcc
	v_cmp_ngt_f32_e32 vcc, s2, v19
	s_nop 1
	v_cndmask_b32_e32 v19, v225, v23, vcc
	v_sub_f32_e32 v19, 1.0, v19
; DI unsigned pk2(float a, float b) { f2_t v = {a, b}; bf2_t r = __builtin_convertvector(v, bf2_t); return __builtin_bit_cast(unsigned, r); }
; DI float bflo(unsigned u) { return (float)__builtin_bit_cast(bf2_t, u)[0]; }
; DI float bfhi(unsigned u) { return (float)__builtin_bit_cast(bf2_t, u)[1]; }
; DI float siluf_(float x) { return x / (1.f + __expf(-x)); }
; DI float geluf_(float x) { return 0.5f * x * (1.f + erff(x * 0.70710678118654752f)); }
; DI void sg_item(const Params& p, int l, int item, char* lds, int dry) {
;     ...
;     for (int a4 = 0; a4 < 4; ++a4) {
;       const int d = db * 32 + 8 * a4 + 4 * h;
;       const uint2 uv = *(const uint2*)(zr + UD + g * 64 + d);
;       uint2* gp = (uint2*)(zr + GD + g * 64 + d);
;       const uint2 gv = *gp;
;       uint2 o;
;       o.x = pk2(geluf_(bflo(uv.x)) * (acc[db][4 * a4] + bsv) * siluf_(bflo(gv.x)),
;                 geluf_(bfhi(uv.x)) * (acc[db][4 * a4 + 1] + bsv) * siluf_(bfhi(gv.x)));
;       o.y = pk2(geluf_(bflo(uv.y)) * (acc[db][4 * a4 + 2] + bsv) * siluf_(bflo(gv.y)),
;                 geluf_(bfhi(uv.y)) * (acc[db][4 * a4 + 3] + bsv) * siluf_(bfhi(gv.y)));
;       if (dry) gp = (uint2*)(p.blkscr + (size_t)blockIdx.x * 8 * 256 + tid + ((db * 4 + a4) >> 1) * 256) + (a4 & 1);
;       *gp = o;
.LBB0_894:
	s_andn2_saveexec_b64 s[0:1], s[0:1]
	v_mul_f32_e32 v19, v5, v5
	v_fmamk_f32 v23, v19, 0xba1345e1, v220
	v_fmaak_f32 v23, v19, v23, 0xbcdac9b8
	v_fmaak_f32 v23, v19, v23, 0x3de703be
	v_fmaak_f32 v23, v19, v23, 0xbec09330
	v_fmaak_f32 v19, v19, v23, 0x3e0375d0
	v_fma_f32 v19, |v5|, v19, |v5|
	s_or_b64 exec, exec, s[0:1]
	s_brev_b32 s2, -2
	v_bfi_b32 v20, s2, v22, v20
	v_mul_f32_e32 v21, 0.5, v21
	v_add_f32_e32 v20, 1.0, v20
	v_mul_f32_e32 v20, v21, v20
	v_add_f32_e32 v12, v12, v34
	v_mul_f32_e32 v12, v12, v20
	s_waitcnt vmcnt(8)
	v_cvt_f32_f16_e32 v20, v193
	v_bfi_b32 v6, s2, v8, v6
	v_mul_f32_e32 v0, 0.5, v0
	v_add_f32_e32 v6, 1.0, v6
	v_mul_f32_e32 v21, 0xbfb8aa3b, v20
	v_exp_f32_e32 v21, v21
	v_mul_f32_e32 v0, v0, v6
	v_add_f32_e32 v6, v10, v34
	v_mul_f32_e32 v0, v6, v0
	v_add_f32_e32 v21, 1.0, v21
	v_div_scale_f32 v22, s[0:1], v21, v21, v20
	v_rcp_f32_e32 v23, v22
	v_cvt_f32_f16_e32 v6, v192
	v_cvt_f32_f16_sdwa v2, v192 dst_sel:DWORD dst_unused:UNUSED_PAD src0_sel:WORD_1
	v_bfi_b32 v35, s2, v9, v7
	v_fma_f32 v24, -v22, v23, 1.0
	v_fmac_f32_e32 v23, v24, v23
	v_div_scale_f32 v24, vcc, v20, v21, v20
	v_mul_f32_e32 v8, 0xbfb8aa3b, v6
	v_mul_f32_e32 v25, v24, v23
	v_exp_f32_e32 v8, v8
	v_fma_f32 v26, -v22, v25, v24
	v_fmac_f32_e32 v25, v26, v23
	v_fma_f32 v22, -v22, v25, v24
	v_div_fmas_f32 v22, v22, v23, v25
	v_add_f32_e32 v8, 1.0, v8
	v_div_fixup_f32 v20, v22, v21, v20
	v_div_scale_f32 v10, s[0:1], v8, v8, v6
	v_mul_f32_e32 v12, v20, v12
	v_rcp_f32_e32 v20, v10
	v_mov_b32_e32 v210, v11
	v_mul_f32_e32 v4, 0.5, v4
	v_cvt_f32_f16_sdwa v3, v193 dst_sel:DWORD dst_unused:UNUSED_PAD src0_sel:WORD_1
	v_fma_f32 v21, -v10, v20, 1.0
	v_fmac_f32_e32 v20, v21, v20
	v_div_scale_f32 v21, vcc, v6, v8, v6
	v_mul_f32_e32 v22, v21, v20
	v_fma_f32 v23, -v10, v22, v21
	v_fmac_f32_e32 v22, v23, v20
	v_fma_f32 v10, -v10, v22, v21
	v_div_fmas_f32 v10, v10, v20, v22
	v_div_fixup_f32 v6, v10, v8, v6
	v_mul_f32_e32 v0, v6, v0
	v_pk_add_f32 v[6:7], v[210:211], v[34:35]
	v_bfi_b32 v35, s2, v19, v5
	v_mul_f32_e32 v4, v4, v7
	v_mul_f32_e32 v4, v6, v4
	v_mul_f32_e32 v6, 0xbfb8aa3b, v2
	v_exp_f32_e32 v6, v6
	v_mov_b32_e32 v210, v13
	v_add_f32_e32 v6, 1.0, v6
	v_div_scale_f32 v7, s[0:1], v6, v6, v2
	v_rcp_f32_e32 v8, v7
	s_nop 0
	v_fma_f32 v9, -v7, v8, 1.0
	v_fmac_f32_e32 v8, v9, v8
	v_div_scale_f32 v9, vcc, v2, v6, v2
	v_mul_f32_e32 v10, v9, v8
	v_fma_f32 v11, -v7, v10, v9
	v_fmac_f32_e32 v10, v11, v8
	v_fma_f32 v7, -v7, v10, v9
	v_div_fmas_f32 v7, v7, v8, v10
	v_div_fixup_f32 v2, v7, v6, v2
	v_mul_f32_e32 v2, v2, v4
	v_cvt_pk_f16_f32 v2, v0, v2
	v_mul_f32_e32 v0, 0.5, v18
	v_pk_add_f32 v[4:5], v[210:211], v[34:35]
	s_nop 0
	v_mul_f32_e32 v0, v0, v5
	v_mul_f32_e32 v0, v4, v0
	v_mul_f32_e32 v4, 0xbfb8aa3b, v3
	v_exp_f32_e32 v4, v4
	s_nop 0
	v_add_f32_e32 v4, 1.0, v4
	v_div_scale_f32 v5, s[0:1], v4, v4, v3
	v_rcp_f32_e32 v6, v5
	s_nop 0
	v_fma_f32 v7, -v5, v6, 1.0
	v_fmac_f32_e32 v6, v7, v6
	v_div_scale_f32 v7, vcc, v3, v4, v3
	v_mul_f32_e32 v8, v7, v6
	v_fma_f32 v9, -v5, v8, v7
	v_fmac_f32_e32 v8, v9, v6
	v_fma_f32 v5, -v5, v8, v7
	v_div_fmas_f32 v5, v5, v6, v8
	v_div_fixup_f32 v3, v5, v4, v3
	v_mul_f32_e32 v0, v3, v0
	v_cvt_pk_f16_f32 v3, v12, v0
	global_store_dwordx2 v[36:37], v[2:3], off offset:96
	s_nop 0
	s_waitcnt vmcnt(8)
	v_cvt_f32_f16_e32 v6, v194
	v_mul_f32_e32 v0, 0x3f3504f3, v6
	v_cmp_nlt_f32_e64 s[0:1], |v0|, 1.0
	s_and_saveexec_b64 s[2:3], s[0:1]
	s_xor_b64 s[0:1], exec, s[2:3]
	s_cbranch_execz .LBB0_898
	v_fma_f32 v7, |v0|, s77, v224
	s_mov_b32 s2, 0x3b7cd369
	v_fma_f32 v7, |v0|, v7, s2
	s_mov_b32 s2, 0xbcc618b2
	v_fma_f32 v7, |v0|, v7, s2
	s_mov_b32 s2, 0x3dda74e4
	v_fma_f32 v7, |v0|, v7, s2
	s_mov_b32 s2, 0x3f228afd
	v_fma_f32 v7, |v0|, v7, s2
	s_mov_b32 s2, 0x3e03c728
	v_fma_f32 v7, |v0|, v7, s2
	v_fma_f32 v7, |v0|, v7, |v0|
	v_mul_f32_e32 v8, 0xbfb8aa3b, v7
	s_mov_b32 s2, 0xbfb8aa3b
	v_fma_f32 v9, v7, s2, -v8
	v_rndne_f32_e32 v10, v8
	v_fmac_f32_e32 v9, 0xb2a5705f, v7
	v_sub_f32_e32 v8, v8, v10
	v_add_f32_e32 v8, v8, v9
	v_cvt_i32_f32_e32 v9, v10
	v_exp_f32_e32 v8, v8
	s_mov_b32 s2, 0x42ce8ed0
	v_cmp_nlt_f32_e32 vcc, s2, v7
	s_mov_b32 s2, 0xc2b17218
	v_ldexp_f32 v8, v8, v9
	v_cndmask_b32_e32 v8, 0, v8, vcc
	v_cmp_ngt_f32_e32 vcc, s2, v7
	s_nop 1
	v_cndmask_b32_e32 v7, v225, v8, vcc
	v_sub_f32_e32 v8, 1.0, v7
.LBB0_898:
	s_andn2_saveexec_b64 s[0:1], s[0:1]
	v_mul_f32_e32 v7, v0, v0
	v_fmamk_f32 v8, v7, 0xba1345e1, v220
	v_fmaak_f32 v8, v7, v8, 0xbcdac9b8
	v_fmaak_f32 v8, v7, v8, 0x3de703be
	v_fmaak_f32 v8, v7, v8, 0xbec09330
	v_fmaak_f32 v7, v7, v8, 0x3e0375d0
	v_fma_f32 v8, |v0|, v7, |v0|
	s_or_b64 exec, exec, s[0:1]
	v_cvt_f32_f16_sdwa v7, v194 dst_sel:DWORD dst_unused:UNUSED_PAD src0_sel:WORD_1
	v_mul_f32_e32 v9, 0x3f3504f3, v7
	v_cmp_nlt_f32_e64 s[0:1], |v9|, 1.0
	s_and_saveexec_b64 s[2:3], s[0:1]
	s_xor_b64 s[0:1], exec, s[2:3]
	s_cbranch_execz .LBB0_902
	v_fma_f32 v4, |v9|, s77, v224
	s_mov_b32 s2, 0x3b7cd369
	v_fma_f32 v4, |v9|, v4, s2
	s_mov_b32 s2, 0xbcc618b2
	v_fma_f32 v4, |v9|, v4, s2
	s_mov_b32 s2, 0x3dda74e4
	v_fma_f32 v4, |v9|, v4, s2
	s_mov_b32 s2, 0x3f228afd
	v_fma_f32 v4, |v9|, v4, s2
	s_mov_b32 s2, 0x3e03c728
	v_fma_f32 v4, |v9|, v4, s2
	v_fma_f32 v4, |v9|, v4, |v9|
	v_mul_f32_e32 v10, 0xbfb8aa3b, v4
	s_mov_b32 s2, 0xbfb8aa3b
	v_fma_f32 v11, v4, s2, -v10
	v_rndne_f32_e32 v12, v10
	v_fmac_f32_e32 v11, 0xb2a5705f, v4
	v_sub_f32_e32 v10, v10, v12
	v_add_f32_e32 v10, v10, v11
	v_cvt_i32_f32_e32 v11, v12
	v_exp_f32_e32 v10, v10
	s_mov_b32 s2, 0x42ce8ed0
	v_cmp_nlt_f32_e32 vcc, s2, v4
	s_mov_b32 s2, 0xc2b17218
	v_ldexp_f32 v10, v10, v11
	v_cndmask_b32_e32 v10, 0, v10, vcc
	v_cmp_ngt_f32_e32 vcc, s2, v4
	s_nop 1
	v_cndmask_b32_e32 v4, v225, v10, vcc
	v_sub_f32_e32 v10, 1.0, v4
; DI unsigned pk2(float a, float b) { f2_t v = {a, b}; bf2_t r = __builtin_convertvector(v, bf2_t); return __builtin_bit_cast(unsigned, r); }
; DI float bflo(unsigned u) { return (float)__builtin_bit_cast(bf2_t, u)[0]; }
; DI float bfhi(unsigned u) { return (float)__builtin_bit_cast(bf2_t, u)[1]; }
; DI float siluf_(float x) { return x / (1.f + __expf(-x)); }
; DI float geluf_(float x) { return 0.5f * x * (1.f + erff(x * 0.70710678118654752f)); }
; DI void sg_item(const Params& p, int l, int item, char* lds, int dry) {
;     ...
;     for (int a4 = 0; a4 < 4; ++a4) {
;       const int d = db * 32 + 8 * a4 + 4 * h;
;       const uint2 uv = *(const uint2*)(zr + UD + g * 64 + d);
;       uint2* gp = (uint2*)(zr + GD + g * 64 + d);
;       const uint2 gv = *gp;
;       uint2 o;
;       o.x = pk2(geluf_(bflo(uv.x)) * (acc[db][4 * a4] + bsv) * siluf_(bflo(gv.x)),
;                 geluf_(bfhi(uv.x)) * (acc[db][4 * a4 + 1] + bsv) * siluf_(bfhi(gv.x)));
;       o.y = pk2(geluf_(bflo(uv.y)) * (acc[db][4 * a4 + 2] + bsv) * siluf_(bflo(gv.y)),
;                 geluf_(bfhi(uv.y)) * (acc[db][4 * a4 + 3] + bsv) * siluf_(bfhi(gv.y)));
;       if (dry) gp = (uint2*)(p.blkscr + (size_t)blockIdx.x * 8 * 256 + tid + ((db * 4 + a4) >> 1) * 256) + (a4 & 1);
;       *gp = o;
.LBB0_902:
	s_andn2_saveexec_b64 s[0:1], s[0:1]
	v_mul_f32_e32 v4, v9, v9
	v_fmamk_f32 v10, v4, 0xba1345e1, v220
	v_fmaak_f32 v10, v4, v10, 0xbcdac9b8
	v_fmaak_f32 v10, v4, v10, 0x3de703be
	v_fmaak_f32 v10, v4, v10, 0xbec09330
	v_fmaak_f32 v4, v4, v10, 0x3e0375d0
	v_fma_f32 v10, |v9|, v4, |v9|
	s_or_b64 exec, exec, s[0:1]
	v_cvt_f32_f16_e32 v4, v195
	v_mul_f32_e32 v11, 0x3f3504f3, v4
	v_cmp_nlt_f32_e64 s[0:1], |v11|, 1.0
	s_and_saveexec_b64 s[2:3], s[0:1]
	s_xor_b64 s[0:1], exec, s[2:3]
	s_cbranch_execz .LBB0_906
	v_fma_f32 v12, |v11|, s77, v224
	s_mov_b32 s2, 0x3b7cd369
	v_fma_f32 v12, |v11|, v12, s2
	s_mov_b32 s2, 0xbcc618b2
	v_fma_f32 v12, |v11|, v12, s2
	s_mov_b32 s2, 0x3dda74e4
	v_fma_f32 v12, |v11|, v12, s2
	s_mov_b32 s2, 0x3f228afd
	v_fma_f32 v12, |v11|, v12, s2
	s_mov_b32 s2, 0x3e03c728
	v_fma_f32 v12, |v11|, v12, s2
	v_fma_f32 v12, |v11|, v12, |v11|
	v_mul_f32_e32 v13, 0xbfb8aa3b, v12
	s_mov_b32 s2, 0xbfb8aa3b
	v_fma_f32 v18, v12, s2, -v13
	v_rndne_f32_e32 v19, v13
	v_fmac_f32_e32 v18, 0xb2a5705f, v12
	v_sub_f32_e32 v13, v13, v19
	v_add_f32_e32 v13, v13, v18
	v_cvt_i32_f32_e32 v18, v19
	v_exp_f32_e32 v13, v13
	s_mov_b32 s2, 0x42ce8ed0
	v_cmp_nlt_f32_e32 vcc, s2, v12
	s_mov_b32 s2, 0xc2b17218
	v_ldexp_f32 v13, v13, v18
	v_cndmask_b32_e32 v13, 0, v13, vcc
	v_cmp_ngt_f32_e32 vcc, s2, v12
	s_nop 1
	v_cndmask_b32_e32 v12, v225, v13, vcc
	v_sub_f32_e32 v12, 1.0, v12
.LBB0_906:
	s_andn2_saveexec_b64 s[0:1], s[0:1]
	v_mul_f32_e32 v12, v11, v11
	v_fmamk_f32 v13, v12, 0xba1345e1, v220
	v_fmaak_f32 v13, v12, v13, 0xbcdac9b8
	v_fmaak_f32 v13, v12, v13, 0x3de703be
	v_fmaak_f32 v13, v12, v13, 0xbec09330
	v_fmaak_f32 v12, v12, v13, 0x3e0375d0
	v_fma_f32 v12, |v11|, v12, |v11|
	s_or_b64 exec, exec, s[0:1]
	v_cvt_f32_f16_sdwa v5, v195 dst_sel:DWORD dst_unused:UNUSED_PAD src0_sel:WORD_1
	v_mul_f32_e32 v13, 0x3f3504f3, v5
	v_cmp_nlt_f32_e64 s[0:1], |v13|, 1.0
	s_and_saveexec_b64 s[2:3], s[0:1]
	s_xor_b64 s[0:1], exec, s[2:3]
	s_cbranch_execz .LBB0_910
	v_fma_f32 v18, |v13|, s77, v224
	s_mov_b32 s2, 0x3b7cd369
	v_fma_f32 v18, |v13|, v18, s2
	s_mov_b32 s2, 0xbcc618b2
	v_fma_f32 v18, |v13|, v18, s2
	s_mov_b32 s2, 0x3dda74e4
	v_fma_f32 v18, |v13|, v18, s2
	s_mov_b32 s2, 0x3f228afd
	v_fma_f32 v18, |v13|, v18, s2
	s_mov_b32 s2, 0x3e03c728
	v_fma_f32 v18, |v13|, v18, s2
	v_fma_f32 v18, |v13|, v18, |v13|
	v_mul_f32_e32 v19, 0xbfb8aa3b, v18
	s_mov_b32 s2, 0xbfb8aa3b
	v_fma_f32 v20, v18, s2, -v19
	v_rndne_f32_e32 v21, v19
	v_fmac_f32_e32 v20, 0xb2a5705f, v18
	v_sub_f32_e32 v19, v19, v21
	v_add_f32_e32 v19, v19, v20
	v_cvt_i32_f32_e32 v20, v21
	v_exp_f32_e32 v19, v19
	s_mov_b32 s2, 0x42ce8ed0
	v_cmp_nlt_f32_e32 vcc, s2, v18
	s_mov_b32 s2, 0xc2b17218
	v_ldexp_f32 v19, v19, v20
	v_cndmask_b32_e32 v19, 0, v19, vcc
	v_cmp_ngt_f32_e32 vcc, s2, v18
	s_nop 1
	v_cndmask_b32_e32 v18, v225, v19, vcc
	v_sub_f32_e32 v18, 1.0, v18
.LBB0_910:
	s_andn2_saveexec_b64 s[0:1], s[0:1]
	v_mul_f32_e32 v18, v13, v13
	v_fmamk_f32 v19, v18, 0xba1345e1, v220
	v_fmaak_f32 v19, v18, v19, 0xbcdac9b8
	v_fmaak_f32 v19, v18, v19, 0x3de703be
	v_fmaak_f32 v19, v18, v19, 0xbec09330
	v_fmaak_f32 v18, v18, v19, 0x3e0375d0
	v_fma_f32 v18, |v13|, v18, |v13|
	s_or_b64 exec, exec, s[0:1]
	s_brev_b32 s0, -2
	v_bfi_b32 v8, s0, v8, v0
	s_waitcnt vmcnt(7)
	v_cvt_f32_f16_sdwa v0, v196 dst_sel:DWORD dst_unused:UNUSED_PAD src0_sel:WORD_1
	v_cvt_f32_f16_e32 v2, v196
	v_bfi_b32 v12, s0, v12, v11
	v_bfi_b32 v9, s0, v10, v9
	v_mul_f32_e32 v11, 0xbfb8aa3b, v0
	v_mul_f32_e32 v10, 0xbfb8aa3b, v2
	v_exp_f32_e32 v10, v10
	v_exp_f32_e32 v11, v11
	v_bfi_b32 v13, s0, v18, v13
	v_pk_mul_f32 v[6:7], v[6:7], 0.5 op_sel_hi:[1,0]
	v_pk_add_f32 v[8:9], v[8:9], 1.0 op_sel_hi:[1,0]
	v_pk_add_f32 v[10:11], v[10:11], 1.0 op_sel_hi:[1,0]
	v_pk_add_f32 v[14:15], v[14:15], v[34:35] op_sel_hi:[1,0]
	v_div_scale_f32 v18, s[0:1], v11, v11, v0
	v_rcp_f32_e32 v19, v18
	v_pk_mul_f32 v[6:7], v[6:7], v[8:9]
	v_pk_mul_f32 v[4:5], v[4:5], 0.5 op_sel_hi:[1,0]
	v_pk_mul_f32 v[6:7], v[14:15], v[6:7]
	v_fma_f32 v20, -v18, v19, 1.0
	v_fmac_f32_e32 v19, v20, v19
	v_div_scale_f32 v20, vcc, v0, v11, v0
	v_mul_f32_e32 v21, v20, v19
	v_fma_f32 v22, -v18, v21, v20
	v_fmac_f32_e32 v21, v22, v19
	v_fma_f32 v18, -v18, v21, v20
	v_div_fmas_f32 v18, v18, v19, v21
	v_div_fixup_f32 v11, v18, v11, v0
	v_div_scale_f32 v0, s[0:1], v10, v10, v2
	v_rcp_f32_e32 v18, v0
	v_pk_add_f32 v[8:9], v[12:13], 1.0 op_sel_hi:[1,0]
	v_fma_f32 v19, -v0, v18, 1.0
	v_fmac_f32_e32 v18, v19, v18
	v_div_scale_f32 v19, vcc, v2, v10, v2
	v_mul_f32_e32 v20, v19, v18
	v_fma_f32 v21, -v0, v20, v19
	v_fmac_f32_e32 v20, v21, v18
	v_fma_f32 v0, -v0, v20, v19
	v_div_fmas_f32 v0, v0, v18, v20
	v_div_fixup_f32 v10, v0, v10, v2
	v_cvt_f32_f16_sdwa v0, v197 dst_sel:DWORD dst_unused:UNUSED_PAD src0_sel:WORD_1
	v_cvt_f32_f16_e32 v3, v197
	v_pk_mul_f32 v[6:7], v[10:11], v[6:7]
	v_pk_mul_f32 v[4:5], v[4:5], v[8:9]
	v_cvt_pk_f16_f32 v2, v6, v7
	v_mul_f32_e32 v6, 0xbfb8aa3b, v3
	v_mul_f32_e32 v7, 0xbfb8aa3b, v0
	v_exp_f32_e32 v6, v6
	v_exp_f32_e32 v7, v7
	v_pk_add_f32 v[8:9], v[16:17], v[34:35] op_sel_hi:[1,0]
	v_pk_add_f32 v[6:7], v[6:7], 1.0 op_sel_hi:[1,0]
	v_pk_mul_f32 v[4:5], v[8:9], v[4:5]
	v_div_scale_f32 v8, s[0:1], v7, v7, v0
	v_rcp_f32_e32 v9, v8
	s_nop 0
	v_fma_f32 v10, -v8, v9, 1.0
	v_fmac_f32_e32 v9, v10, v9
	v_div_scale_f32 v10, vcc, v0, v7, v0
	v_mul_f32_e32 v11, v10, v9
	v_fma_f32 v12, -v8, v11, v10
	v_fmac_f32_e32 v11, v12, v9
	v_fma_f32 v8, -v8, v11, v10
	v_div_fmas_f32 v8, v8, v9, v11
	v_div_fixup_f32 v7, v8, v7, v0
	v_div_scale_f32 v0, s[0:1], v6, v6, v3
	v_rcp_f32_e32 v8, v0
	s_mov_b64 s[0:1], 0
	v_fma_f32 v9, -v0, v8, 1.0
	v_fmac_f32_e32 v8, v9, v8
	v_div_scale_f32 v9, vcc, v3, v6, v3
	v_mul_f32_e32 v10, v9, v8
	v_fma_f32 v11, -v0, v10, v9
	v_fmac_f32_e32 v10, v11, v8
	v_fma_f32 v0, -v0, v10, v9
	v_div_fmas_f32 v0, v0, v8, v10
	v_div_fixup_f32 v6, v0, v6, v3
	v_pk_mul_f32 v[4:5], v[6:7], v[4:5]
	s_nop 0
	v_cvt_pk_f16_f32 v3, v4, v5
	global_store_dwordx2 v[36:37], v[2:3], off offset:112
